# GEMM units: first K-loop iteration peeled with SrcC=0 on first-touch MFMAs, removing 128 accumulator-clear v_mov per unit
# speedup vs baseline: 1.0111x; 1.0074x over previous
; #define PG8_STAGE(bufoff, gbase, voff) do { _Pragma("unroll") for (int _i = 0; _i < 2; ++_i) \
;         __builtin_amdgcn_global_load_lds((const unsigned*)((const char*)(gbase) + (voff)[_i]), (LAS unsigned*)(lds + (bufoff) + ldsw + _i * 8192), 16, 0, 0); } while (0)
; #define PG8_WAIT_V(n) asm volatile("s_waitcnt vmcnt(" #n ")" ::: "memory")
; #define PG8_WAIT_L(n) asm volatile("s_waitcnt lgkmcnt(" #n ")" ::: "memory")
; template <class Epi>
; __device__ __forceinline__ void gemm_phase(LAS unsigned char* lds, const Gemm g, const StaticOrder& S, const Epi& E, int wv) {
;     ...
;         const bool has_next = S.next(ui + 1, nxt);
;         const char* nA = has_next ? (const char*)g.A + (size_t)nxt.pm * tstepA : cA; const char* nB = has_next ? (const char*)g.Bt + (size_t)nxt.pn * tstepB : cB;
;         for (int t = 0; t < nt; t += 2) {
;             const bool last = (t == nt - 2);
;             const char* a1 = cA + (size_t)(t + 1) * kstep;
;             const char* a2 = last ? nA : cA + (size_t)(t + 2) * kstep; const char* b2 = last ? nB : cB + (size_t)(t + 2) * kstep;
;             const char* a3 = a2 + kstep; const char* b3 = b2 + kstep;
;             PG8_LDB(B0, 0, 0); PG8_SCHED; PG8_LDA(At, 0, 0); PG8_STAGE(PG8_SA(1, 1), a1 + hstep, voffA);
;             PG8_WAIT_L(8); PG8_BAR; PG8_WAIT_L(0); PG8_MMA(0, 0, At, B0); PG8_BAR; PG8_SCHED;
;             PG8_LDB(B1, 0, 1); PG8_STAGE(PG8_SB(0, 0), b2, voffB);
;             PG8_BAR; PG8_WAIT_L(0); PG8_MMA(0, 1, At, B1); PG8_BAR;
;             PG8_LDA(At, 0, 1); PG8_STAGE(PG8_SA(0, 0), a2, voffA);
;             PG8_BAR; PG8_WAIT_L(0); PG8_MMA(1, 0, At, B0); PG8_BAR; PG8_SCHED;
;             PG8_STAGE(PG8_SB(0, 1), b2 + hstep, voffB);
;             PG8_WAIT_V(6); PG8_BAR; PG8_MMA(1, 1, At, B1); PG8_BAR;
;             PG8_LDB(B0, 1, 0); PG8_SCHED; PG8_LDA(At, 1, 0); PG8_STAGE(PG8_SA(0, 1), a2 + hstep, voffA);
;             PG8_WAIT_L(8); PG8_BAR; PG8_WAIT_L(0); PG8_MMA(0, 0, At, B0); PG8_BAR; PG8_SCHED;
;             PG8_LDB(B1, 1, 1); PG8_STAGE(PG8_SB(1, 0), b3, voffB);
;             PG8_BAR; PG8_WAIT_L(0); PG8_MMA(0, 1, At, B1); PG8_BAR;
;             PG8_LDA(At, 1, 1); PG8_STAGE(PG8_SA(1, 0), a3, voffA);
;             PG8_BAR; PG8_WAIT_L(0); PG8_MMA(1, 0, At, B0); PG8_BAR; PG8_SCHED;
;             PG8_STAGE(PG8_SB(1, 1), b3 + hstep, voffB);
;             PG8_WAIT_V(6); PG8_BAR; PG8_MMA(1, 1, At, B1); PG8_BAR;
.LBB0_214:
	s_ashr_i32 s35, s34, 31
	v_cmp_lt_i64_e32 vcc, s[36:37], v[142:143]
	s_lshl_b64 s[36:37], s[34:35], 19
	s_add_u32 s36, s27, s36
	s_addc_u32 s37, s48, s37
	s_and_b64 s[38:39], vcc, exec
	s_cselect_b32 s7, s37, s41
	s_cselect_b32 s9, s36, s40
	s_ashr_i32 s31, s30, 31
	s_lshl_b64 s[38:39], s[30:31], 19
	s_add_u32 s38, s14, s38
	s_addc_u32 s39, s15, s39
	s_and_b64 s[44:45], vcc, exec
	s_cselect_b32 s31, s39, s43
	s_cselect_b32 s35, s38, s42
	s_add_u32 s68, s42, 0x100
	s_addc_u32 s69, s43, 0
	s_mov_b32 s70, -2
	ds_read_b128 v[146:149], v153
	ds_read_b128 v[156:159], v153 offset:1024
	ds_read_b128 v[160:163], v153 offset:2048
	ds_read_b128 v[164:167], v153 offset:3072
	s_add_u32 s42, s40, 0x100
	s_addc_u32 s43, s41, 0
	s_cmp_eq_u32 s70, 12
	s_cselect_b32 s47, s7, s43
	s_cselect_b32 s46, s9, s42
	s_cselect_b32 s45, s31, s69
	s_cselect_b32 s44, s35, s68
	ds_read_b128 v[168:171], v154
	ds_read_b128 v[172:175], v154 offset:1024
	ds_read_b128 v[176:179], v154 offset:2048
	ds_read_b128 v[180:183], v154 offset:3072
	ds_read_b128 v[184:187], v154 offset:4096
	ds_read_b128 v[188:191], v154 offset:5120
	ds_read_b128 v[192:195], v154 offset:6144
	ds_read_b128 v[196:199], v154 offset:7168
	ds_read_b128 v[200:203], v155
	ds_read_b128 v[204:207], v155 offset:1024
	ds_read_b128 v[208:211], v155 offset:2048
	ds_read_b128 v[212:215], v155 offset:3072
	v_lshl_add_u64 v[252:253], s[40:41], 0, v[138:139]
	s_add_i32 m0, s50, 0xc000
	s_nop 0
	global_load_lds_dwordx4 v[252:253], off
	v_lshl_add_u64 v[252:253], s[40:41], 0, v[140:141]
	s_add_i32 m0, s50, 0xe000
	s_nop 0
	global_load_lds_dwordx4 v[252:253], off
	s_waitcnt vmcnt(8)
	s_waitcnt lgkmcnt(0)
	s_barrier
	s_setprio 1
	v_mfma_f32_16x16x32_bf16 v[124:127], v[146:149], v[168:171], 0
	v_mfma_f32_16x16x32_bf16 v[120:123], v[160:163], v[168:171], 0
	v_mfma_f32_16x16x32_bf16 v[108:111], v[146:149], v[176:179], 0
	v_mfma_f32_16x16x32_bf16 v[104:107], v[160:163], v[176:179], 0
	v_mfma_f32_16x16x32_bf16 v[92:95], v[146:149], v[184:187], 0
	v_mfma_f32_16x16x32_bf16 v[88:91], v[160:163], v[184:187], 0
	v_mfma_f32_16x16x32_bf16 v[76:79], v[146:149], v[192:195], 0
	v_mfma_f32_16x16x32_bf16 v[72:75], v[160:163], v[192:195], 0
	v_mfma_f32_16x16x32_bf16 v[124:127], v[156:159], v[172:175], v[124:127]
	v_mfma_f32_16x16x32_bf16 v[120:123], v[164:167], v[172:175], v[120:123]
	v_mfma_f32_16x16x32_bf16 v[108:111], v[156:159], v[180:183], v[108:111]
	v_mfma_f32_16x16x32_bf16 v[104:107], v[164:167], v[180:183], v[104:107]
	v_mfma_f32_16x16x32_bf16 v[92:95], v[156:159], v[188:191], v[92:95]
	v_mfma_f32_16x16x32_bf16 v[88:91], v[164:167], v[188:191], v[88:91]
	v_mfma_f32_16x16x32_bf16 v[76:79], v[156:159], v[196:199], v[76:79]
	v_mfma_f32_16x16x32_bf16 v[72:75], v[164:167], v[196:199], v[72:75]
	v_mfma_f32_16x16x32_bf16 v[116:119], v[200:203], v[168:171], 0
	v_mfma_f32_16x16x32_bf16 v[112:115], v[208:211], v[168:171], 0
	v_mfma_f32_16x16x32_bf16 v[100:103], v[200:203], v[176:179], 0
	v_mfma_f32_16x16x32_bf16 v[96:99], v[208:211], v[176:179], 0
	v_mfma_f32_16x16x32_bf16 v[84:87], v[200:203], v[184:187], 0
	v_mfma_f32_16x16x32_bf16 v[80:83], v[208:211], v[184:187], 0
	v_mfma_f32_16x16x32_bf16 v[68:71], v[200:203], v[192:195], 0
	v_mfma_f32_16x16x32_bf16 v[64:67], v[208:211], v[192:195], 0
	v_mfma_f32_16x16x32_bf16 v[116:119], v[204:207], v[172:175], v[116:119]
	v_mfma_f32_16x16x32_bf16 v[112:115], v[212:215], v[172:175], v[112:115]
	v_mfma_f32_16x16x32_bf16 v[100:103], v[204:207], v[180:183], v[100:103]
	v_mfma_f32_16x16x32_bf16 v[96:99], v[212:215], v[180:183], v[96:99]
	v_mfma_f32_16x16x32_bf16 v[84:87], v[204:207], v[188:191], v[84:87]
	v_mfma_f32_16x16x32_bf16 v[80:83], v[212:215], v[188:191], v[80:83]
	v_mfma_f32_16x16x32_bf16 v[68:71], v[204:207], v[196:199], v[68:71]
	v_mfma_f32_16x16x32_bf16 v[64:67], v[212:215], v[196:199], v[64:67]
	s_setprio 0
	s_barrier
	ds_read_b128 v[168:171], v154 offset:16384
	ds_read_b128 v[172:175], v154 offset:17408
	ds_read_b128 v[176:179], v154 offset:18432
	ds_read_b128 v[180:183], v154 offset:19456
	ds_read_b128 v[184:187], v154 offset:20480
	ds_read_b128 v[188:191], v154 offset:21504
	ds_read_b128 v[192:195], v154 offset:22528
	ds_read_b128 v[196:199], v154 offset:23552
	s_add_i32 s40, s65, s49
	v_lshl_add_u64 v[150:151], s[44:45], 0, v[130:131]
	s_mov_b32 m0, s40
	s_nop 0
	global_load_lds_dwordx4 v[150:151], off
	v_lshl_add_u64 v[216:217], s[44:45], 0, v[134:135]
	s_add_i32 m0, s40, 0x2000
	s_nop 0
	global_load_lds_dwordx4 v[216:217], off
	s_mov_b32 m0, s50
	v_lshl_add_u64 v[218:219], s[46:47], 0, v[128:129]
	global_load_lds_dwordx4 v[218:219], off
	v_lshl_add_u64 v[220:221], s[46:47], 0, v[132:133]
	s_mov_b32 m0, s51
	s_nop 0
	global_load_lds_dwordx4 v[220:221], off
	s_add_u32 s40, s44, 0x40000
	s_addc_u32 s41, s45, 0
	s_add_i32 s71, s66, s49
	v_lshl_add_u64 v[254:255], s[40:41], 0, v[130:131]
	s_mov_b32 m0, s71
	s_nop 0
	global_load_lds_dwordx4 v[254:255], off
	v_lshl_add_u64 v[254:255], s[40:41], 0, v[134:135]
	s_add_i32 m0, s71, 0x2000
	s_nop 0
	global_load_lds_dwordx4 v[254:255], off
	s_waitcnt vmcnt(8)
	s_waitcnt lgkmcnt(0)
	s_barrier
; #define PG8_STAGE(bufoff, gbase, voff) do { _Pragma("unroll") for (int _i = 0; _i < 2; ++_i) \
;         __builtin_amdgcn_global_load_lds((const unsigned*)((const char*)(gbase) + (voff)[_i]), (LAS unsigned*)(lds + (bufoff) + ldsw + _i * 8192), 16, 0, 0); } while (0)
; #define PG8_LDA(dst, b, h) do { _Pragma("unroll") for (int m = 0; m < 4; ++m) _Pragma("unroll") for (int k = 0; k < 2; ++k) dst[m][k] = *(const LAS bf16x8*)(lds + PG8_SA(b, h) + aoff + m * 2048 + k * 1024); } while (0)
; #define PG8_WAIT_V(n) asm volatile("s_waitcnt vmcnt(" #n ")" ::: "memory")
; #define PG8_WAIT_L(n) asm volatile("s_waitcnt lgkmcnt(" #n ")" ::: "memory")
; template <class Epi>
; __device__ __forceinline__ void gemm_phase(LAS unsigned char* lds, const Gemm g, const StaticOrder& S, const Epi& E, int wv) {
;     ...
;         for (int t = 0; t < nt; t += 2) {
;             const bool last = (t == nt - 2);
;             const char* a1 = cA + (size_t)(t + 1) * kstep;
;             const char* a2 = last ? nA : cA + (size_t)(t + 2) * kstep; const char* b2 = last ? nB : cB + (size_t)(t + 2) * kstep;
;             const char* a3 = a2 + kstep; const char* b3 = b2 + kstep;
;             PG8_LDB(B0, 0, 0); PG8_SCHED; PG8_LDA(At, 0, 0); PG8_STAGE(PG8_SA(1, 1), a1 + hstep, voffA);
;             PG8_WAIT_L(8); PG8_BAR; PG8_WAIT_L(0); PG8_MMA(0, 0, At, B0); PG8_BAR; PG8_SCHED;
;             PG8_LDB(B1, 0, 1); PG8_STAGE(PG8_SB(0, 0), b2, voffB);
;             PG8_BAR; PG8_WAIT_L(0); PG8_MMA(0, 1, At, B1); PG8_BAR;
;             PG8_LDA(At, 0, 1); PG8_STAGE(PG8_SA(0, 0), a2, voffA);
;             PG8_BAR; PG8_WAIT_L(0); PG8_MMA(1, 0, At, B0); PG8_BAR; PG8_SCHED;
;             PG8_STAGE(PG8_SB(0, 1), b2 + hstep, voffB);
;             PG8_WAIT_V(6); PG8_BAR; PG8_MMA(1, 1, At, B1); PG8_BAR;
;             PG8_LDB(B0, 1, 0); PG8_SCHED; PG8_LDA(At, 1, 0); PG8_STAGE(PG8_SA(0, 1), a2 + hstep, voffA);
;             PG8_WAIT_L(8); PG8_BAR; PG8_WAIT_L(0); PG8_MMA(0, 0, At, B0); PG8_BAR; PG8_SCHED;
;             PG8_LDB(B1, 1, 1); PG8_STAGE(PG8_SB(1, 0), b3, voffB);
;             PG8_BAR; PG8_WAIT_L(0); PG8_MMA(0, 1, At, B1); PG8_BAR;
;             PG8_LDA(At, 1, 1); PG8_STAGE(PG8_SA(1, 0), a3, voffA);
;             PG8_BAR; PG8_WAIT_L(0); PG8_MMA(1, 0, At, B0); PG8_BAR; PG8_SCHED;
;             PG8_STAGE(PG8_SB(1, 1), b3 + hstep, voffB);
;             PG8_WAIT_V(6); PG8_BAR; PG8_MMA(1, 1, At, B1); PG8_BAR;
	s_setprio 1
	v_mfma_f32_16x16x32_bf16 v[60:63], v[146:149], v[168:171], 0
	v_mfma_f32_16x16x32_bf16 v[56:59], v[160:163], v[168:171], 0
	v_mfma_f32_16x16x32_bf16 v[44:47], v[146:149], v[176:179], 0
	v_mfma_f32_16x16x32_bf16 v[40:43], v[160:163], v[176:179], 0
	v_mfma_f32_16x16x32_bf16 v[28:31], v[146:149], v[184:187], 0
	v_mfma_f32_16x16x32_bf16 v[24:27], v[160:163], v[184:187], 0
	v_mfma_f32_16x16x32_bf16 v[12:15], v[146:149], v[192:195], 0
	v_mfma_f32_16x16x32_bf16 v[8:11], v[160:163], v[192:195], 0
	v_mfma_f32_16x16x32_bf16 v[60:63], v[156:159], v[172:175], v[60:63]
	v_mfma_f32_16x16x32_bf16 v[56:59], v[164:167], v[172:175], v[56:59]
	v_mfma_f32_16x16x32_bf16 v[44:47], v[156:159], v[180:183], v[44:47]
	v_mfma_f32_16x16x32_bf16 v[40:43], v[164:167], v[180:183], v[40:43]
	v_mfma_f32_16x16x32_bf16 v[28:31], v[156:159], v[188:191], v[28:31]
	v_mfma_f32_16x16x32_bf16 v[24:27], v[164:167], v[188:191], v[24:27]
	v_mfma_f32_16x16x32_bf16 v[12:15], v[156:159], v[196:199], v[12:15]
	v_mfma_f32_16x16x32_bf16 v[8:11], v[164:167], v[196:199], v[8:11]
	v_mfma_f32_16x16x32_bf16 v[52:55], v[200:203], v[168:171], 0
	v_mfma_f32_16x16x32_bf16 v[48:51], v[208:211], v[168:171], 0
	v_mfma_f32_16x16x32_bf16 v[36:39], v[200:203], v[176:179], 0
	v_mfma_f32_16x16x32_bf16 v[32:35], v[208:211], v[176:179], 0
	v_mfma_f32_16x16x32_bf16 v[20:23], v[200:203], v[184:187], 0
	v_mfma_f32_16x16x32_bf16 v[16:19], v[208:211], v[184:187], 0
	v_mfma_f32_16x16x32_bf16 v[4:7], v[200:203], v[192:195], 0
	v_mfma_f32_16x16x32_bf16 v[0:3], v[208:211], v[192:195], 0
	v_mfma_f32_16x16x32_bf16 v[52:55], v[204:207], v[172:175], v[52:55]
	v_mfma_f32_16x16x32_bf16 v[48:51], v[212:215], v[172:175], v[48:51]
	v_mfma_f32_16x16x32_bf16 v[36:39], v[204:207], v[180:183], v[36:39]
	v_mfma_f32_16x16x32_bf16 v[32:35], v[212:215], v[180:183], v[32:35]
	v_mfma_f32_16x16x32_bf16 v[20:23], v[204:207], v[188:191], v[20:23]
	v_mfma_f32_16x16x32_bf16 v[16:19], v[212:215], v[188:191], v[16:19]
	v_mfma_f32_16x16x32_bf16 v[4:7], v[204:207], v[196:199], v[4:7]
	v_mfma_f32_16x16x32_bf16 v[0:3], v[212:215], v[196:199], v[0:3]
	s_setprio 0
	s_add_i32 s71, 0, 0x18000
	v_add_u32_e32 v136, s71, v152
	s_barrier
	ds_read_b128 v[146:149], v136
	ds_read_b128 v[156:159], v136 offset:1024
	ds_read_b128 v[160:163], v136 offset:2048
	ds_read_b128 v[164:167], v136 offset:3072
	s_add_u32 s40, s46, 0x40000
	s_addc_u32 s41, s47, 0
	ds_read_b128 v[168:171], v154 offset:32768
	ds_read_b128 v[172:175], v154 offset:33792
	ds_read_b128 v[176:179], v154 offset:34816
	ds_read_b128 v[180:183], v154 offset:35840
	ds_read_b128 v[184:187], v154 offset:36864
	ds_read_b128 v[188:191], v154 offset:37888
	ds_read_b128 v[192:195], v154 offset:38912
	ds_read_b128 v[196:199], v154 offset:39936
	s_mov_b32 m0, s52
	v_lshl_add_u64 v[252:253], s[40:41], 0, v[128:129]
	global_load_lds_dwordx4 v[252:253], off
	v_lshl_add_u64 v[252:253], s[40:41], 0, v[132:133]
	s_mov_b32 m0, s53
	s_nop 0
	global_load_lds_dwordx4 v[252:253], off
	s_add_i32 s46, 0, 0x1c000
	v_add_u32_e32 v136, s46, v152
	ds_read_b128 v[200:203], v136
	ds_read_b128 v[204:207], v136 offset:1024
	ds_read_b128 v[208:211], v136 offset:2048
	ds_read_b128 v[212:215], v136 offset:3072
	s_waitcnt vmcnt(8)
	s_waitcnt lgkmcnt(0)
	s_barrier
	s_setprio 1
	v_mfma_f32_16x16x32_bf16 v[124:127], v[146:149], v[168:171], v[124:127]
	v_mfma_f32_16x16x32_bf16 v[120:123], v[160:163], v[168:171], v[120:123]
	v_mfma_f32_16x16x32_bf16 v[108:111], v[146:149], v[176:179], v[108:111]
	v_mfma_f32_16x16x32_bf16 v[104:107], v[160:163], v[176:179], v[104:107]
	v_mfma_f32_16x16x32_bf16 v[92:95], v[146:149], v[184:187], v[92:95]
	v_mfma_f32_16x16x32_bf16 v[88:91], v[160:163], v[184:187], v[88:91]
	v_mfma_f32_16x16x32_bf16 v[76:79], v[146:149], v[192:195], v[76:79]
	v_mfma_f32_16x16x32_bf16 v[72:75], v[160:163], v[192:195], v[72:75]
	v_mfma_f32_16x16x32_bf16 v[124:127], v[156:159], v[172:175], v[124:127]
	v_mfma_f32_16x16x32_bf16 v[120:123], v[164:167], v[172:175], v[120:123]
	v_mfma_f32_16x16x32_bf16 v[108:111], v[156:159], v[180:183], v[108:111]
	v_mfma_f32_16x16x32_bf16 v[104:107], v[164:167], v[180:183], v[104:107]
	v_mfma_f32_16x16x32_bf16 v[92:95], v[156:159], v[188:191], v[92:95]
	v_mfma_f32_16x16x32_bf16 v[88:91], v[164:167], v[188:191], v[88:91]
	v_mfma_f32_16x16x32_bf16 v[76:79], v[156:159], v[196:199], v[76:79]
	v_mfma_f32_16x16x32_bf16 v[72:75], v[164:167], v[196:199], v[72:75]
	v_mfma_f32_16x16x32_bf16 v[116:119], v[200:203], v[168:171], v[116:119]
	v_mfma_f32_16x16x32_bf16 v[112:115], v[208:211], v[168:171], v[112:115]
	v_mfma_f32_16x16x32_bf16 v[100:103], v[200:203], v[176:179], v[100:103]
	v_mfma_f32_16x16x32_bf16 v[96:99], v[208:211], v[176:179], v[96:99]
	v_mfma_f32_16x16x32_bf16 v[84:87], v[200:203], v[184:187], v[84:87]
	v_mfma_f32_16x16x32_bf16 v[80:83], v[208:211], v[184:187], v[80:83]
	v_mfma_f32_16x16x32_bf16 v[68:71], v[200:203], v[192:195], v[68:71]
	v_mfma_f32_16x16x32_bf16 v[64:67], v[208:211], v[192:195], v[64:67]
	v_mfma_f32_16x16x32_bf16 v[116:119], v[204:207], v[172:175], v[116:119]
	v_mfma_f32_16x16x32_bf16 v[112:115], v[212:215], v[172:175], v[112:115]
	v_mfma_f32_16x16x32_bf16 v[100:103], v[204:207], v[180:183], v[100:103]
	v_mfma_f32_16x16x32_bf16 v[96:99], v[212:215], v[180:183], v[96:99]
	v_mfma_f32_16x16x32_bf16 v[84:87], v[204:207], v[188:191], v[84:87]
	v_mfma_f32_16x16x32_bf16 v[80:83], v[212:215], v[188:191], v[80:83]
	v_mfma_f32_16x16x32_bf16 v[68:71], v[204:207], v[196:199], v[68:71]
	v_mfma_f32_16x16x32_bf16 v[64:67], v[212:215], v[196:199], v[64:67]
	s_setprio 0
	s_barrier
; #define PG8_STAGE(bufoff, gbase, voff) do { _Pragma("unroll") for (int _i = 0; _i < 2; ++_i) \
;         __builtin_amdgcn_global_load_lds((const unsigned*)((const char*)(gbase) + (voff)[_i]), (LAS unsigned*)(lds + (bufoff) + ldsw + _i * 8192), 16, 0, 0); } while (0)
; #define PG8_LDA(dst, b, h) do { _Pragma("unroll") for (int m = 0; m < 4; ++m) _Pragma("unroll") for (int k = 0; k < 2; ++k) dst[m][k] = *(const LAS bf16x8*)(lds + PG8_SA(b, h) + aoff + m * 2048 + k * 1024); } while (0)
; #define PG8_WAIT_V(n) asm volatile("s_waitcnt vmcnt(" #n ")" ::: "memory")
; #define PG8_WAIT_L(n) asm volatile("s_waitcnt lgkmcnt(" #n ")" ::: "memory")
; template <class Epi>
; __device__ __forceinline__ void gemm_phase(LAS unsigned char* lds, const Gemm g, const StaticOrder& S, const Epi& E, int wv) {
;     ...
;         for (int t = 0; t < nt; t += 2) {
;             const bool last = (t == nt - 2);
;             const char* a1 = cA + (size_t)(t + 1) * kstep;
;             const char* a2 = last ? nA : cA + (size_t)(t + 2) * kstep; const char* b2 = last ? nB : cB + (size_t)(t + 2) * kstep;
;             const char* a3 = a2 + kstep; const char* b3 = b2 + kstep;
;             PG8_LDB(B0, 0, 0); PG8_SCHED; PG8_LDA(At, 0, 0); PG8_STAGE(PG8_SA(1, 1), a1 + hstep, voffA);
;             PG8_WAIT_L(8); PG8_BAR; PG8_WAIT_L(0); PG8_MMA(0, 0, At, B0); PG8_BAR; PG8_SCHED;
;             PG8_LDB(B1, 0, 1); PG8_STAGE(PG8_SB(0, 0), b2, voffB);
;             PG8_BAR; PG8_WAIT_L(0); PG8_MMA(0, 1, At, B1); PG8_BAR;
;             PG8_LDA(At, 0, 1); PG8_STAGE(PG8_SA(0, 0), a2, voffA);
;             PG8_BAR; PG8_WAIT_L(0); PG8_MMA(1, 0, At, B0); PG8_BAR; PG8_SCHED;
;             PG8_STAGE(PG8_SB(0, 1), b2 + hstep, voffB);
;             PG8_WAIT_V(6); PG8_BAR; PG8_MMA(1, 1, At, B1); PG8_BAR;
;             PG8_LDB(B0, 1, 0); PG8_SCHED; PG8_LDA(At, 1, 0); PG8_STAGE(PG8_SA(0, 1), a2 + hstep, voffA);
;             PG8_WAIT_L(8); PG8_BAR; PG8_WAIT_L(0); PG8_MMA(0, 0, At, B0); PG8_BAR; PG8_SCHED;
;             PG8_LDB(B1, 1, 1); PG8_STAGE(PG8_SB(1, 0), b3, voffB);
;             PG8_BAR; PG8_WAIT_L(0); PG8_MMA(0, 1, At, B1); PG8_BAR;
;             PG8_LDA(At, 1, 1); PG8_STAGE(PG8_SA(1, 0), a3, voffA);
;             PG8_BAR; PG8_WAIT_L(0); PG8_MMA(1, 0, At, B0); PG8_BAR; PG8_SCHED;
;             PG8_STAGE(PG8_SB(1, 1), b3 + hstep, voffB);
;             PG8_WAIT_V(6); PG8_BAR; PG8_MMA(1, 1, At, B1); PG8_BAR;
	ds_read_b128 v[168:171], v154 offset:49152
	ds_read_b128 v[172:175], v154 offset:50176
	ds_read_b128 v[176:179], v154 offset:51200
	ds_read_b128 v[180:183], v154 offset:52224
	ds_read_b128 v[184:187], v154 offset:53248
	ds_read_b128 v[188:191], v154 offset:54272
	ds_read_b128 v[192:195], v154 offset:55296
	ds_read_b128 v[196:199], v154 offset:56320
	s_add_i32 s40, s71, s49
	v_lshl_add_u64 v[150:151], v[150:151], 0, s[28:29]
	s_mov_b32 m0, s40
	s_nop 0
	global_load_lds_dwordx4 v[150:151], off
	v_lshl_add_u64 v[150:151], v[216:217], 0, s[28:29]
	s_add_i32 m0, s40, 0x2000
	s_nop 0
	global_load_lds_dwordx4 v[150:151], off
	s_mov_b32 m0, s58
	v_lshl_add_u64 v[150:151], v[218:219], 0, s[28:29]
	global_load_lds_dwordx4 v[150:151], off
	v_lshl_add_u64 v[150:151], v[220:221], 0, s[28:29]
	s_mov_b32 m0, s59
	s_nop 0
	global_load_lds_dwordx4 v[150:151], off
	s_add_u32 s40, s44, 0x40080
	s_addc_u32 s41, s45, 0
	s_add_i32 s44, s46, s49
	v_lshl_add_u64 v[254:255], s[40:41], 0, v[130:131]
	s_mov_b32 m0, s44
	s_nop 0
	global_load_lds_dwordx4 v[254:255], off
	v_lshl_add_u64 v[254:255], s[40:41], 0, v[134:135]
	s_add_i32 m0, s44, 0x2000
	s_nop 0
	global_load_lds_dwordx4 v[254:255], off
	s_waitcnt vmcnt(8)
	s_waitcnt lgkmcnt(0)
	s_barrier
	s_setprio 1
	v_mfma_f32_16x16x32_bf16 v[60:63], v[146:149], v[168:171], v[60:63]
	v_mfma_f32_16x16x32_bf16 v[56:59], v[160:163], v[168:171], v[56:59]
	v_mfma_f32_16x16x32_bf16 v[44:47], v[146:149], v[176:179], v[44:47]
	v_mfma_f32_16x16x32_bf16 v[40:43], v[160:163], v[176:179], v[40:43]
	v_mfma_f32_16x16x32_bf16 v[28:31], v[146:149], v[184:187], v[28:31]
	v_mfma_f32_16x16x32_bf16 v[24:27], v[160:163], v[184:187], v[24:27]
	v_mfma_f32_16x16x32_bf16 v[12:15], v[146:149], v[192:195], v[12:15]
	v_mfma_f32_16x16x32_bf16 v[8:11], v[160:163], v[192:195], v[8:11]
	v_mfma_f32_16x16x32_bf16 v[60:63], v[156:159], v[172:175], v[60:63]
	v_mfma_f32_16x16x32_bf16 v[56:59], v[164:167], v[172:175], v[56:59]
	v_mfma_f32_16x16x32_bf16 v[44:47], v[156:159], v[180:183], v[44:47]
	v_mfma_f32_16x16x32_bf16 v[40:43], v[164:167], v[180:183], v[40:43]
	v_mfma_f32_16x16x32_bf16 v[28:31], v[156:159], v[188:191], v[28:31]
	v_mfma_f32_16x16x32_bf16 v[24:27], v[164:167], v[188:191], v[24:27]
	v_mfma_f32_16x16x32_bf16 v[12:15], v[156:159], v[196:199], v[12:15]
	v_mfma_f32_16x16x32_bf16 v[8:11], v[164:167], v[196:199], v[8:11]
	v_mfma_f32_16x16x32_bf16 v[52:55], v[200:203], v[168:171], v[52:55]
	v_mfma_f32_16x16x32_bf16 v[48:51], v[208:211], v[168:171], v[48:51]
	v_mfma_f32_16x16x32_bf16 v[36:39], v[200:203], v[176:179], v[36:39]
	v_mfma_f32_16x16x32_bf16 v[32:35], v[208:211], v[176:179], v[32:35]
	v_mfma_f32_16x16x32_bf16 v[20:23], v[200:203], v[184:187], v[20:23]
	v_mfma_f32_16x16x32_bf16 v[16:19], v[208:211], v[184:187], v[16:19]
	v_mfma_f32_16x16x32_bf16 v[4:7], v[200:203], v[192:195], v[4:7]
	v_mfma_f32_16x16x32_bf16 v[0:3], v[208:211], v[192:195], v[0:3]
	v_mfma_f32_16x16x32_bf16 v[52:55], v[204:207], v[172:175], v[52:55]
	v_mfma_f32_16x16x32_bf16 v[48:51], v[212:215], v[172:175], v[48:51]
	v_mfma_f32_16x16x32_bf16 v[36:39], v[204:207], v[180:183], v[36:39]
	v_mfma_f32_16x16x32_bf16 v[32:35], v[212:215], v[180:183], v[32:35]
	v_mfma_f32_16x16x32_bf16 v[20:23], v[204:207], v[188:191], v[20:23]
	v_mfma_f32_16x16x32_bf16 v[16:19], v[212:215], v[188:191], v[16:19]
	v_mfma_f32_16x16x32_bf16 v[4:7], v[204:207], v[196:199], v[4:7]
	v_mfma_f32_16x16x32_bf16 v[0:3], v[212:215], v[196:199], v[0:3]
	s_setprio 0
	s_add_i32 s70, s70, 2
	s_add_u32 s68, s68, 0x100
	s_addc_u32 s69, s69, 0
	s_cmp_gt_u32 s70, 13
	s_mov_b64 s[40:41], s[42:43]
	s_barrier

; #define PG8_STAGE(bufoff, gbase, voff) do { _Pragma("unroll") for (int _i = 0; _i < 2; ++_i) \
;         __builtin_amdgcn_global_load_lds((const unsigned*)((const char*)(gbase) + (voff)[_i]), (LAS unsigned*)(lds + (bufoff) + ldsw + _i * 8192), 16, 0, 0); } while (0)
; #define PG8_WAIT_V(n) asm volatile("s_waitcnt vmcnt(" #n ")" ::: "memory")
; #define PG8_WAIT_L(n) asm volatile("s_waitcnt lgkmcnt(" #n ")" ::: "memory")
; template <class Epi>
; __device__ __forceinline__ void gemm_phase(LAS unsigned char* lds, const Gemm g, const StaticOrder& S, const Epi& E, int wv) {
;     ...
;         const bool has_next = S.next(ui + 1, nxt);
;         const char* nA = has_next ? (const char*)g.A + (size_t)nxt.pm * tstepA : cA; const char* nB = has_next ? (const char*)g.Bt + (size_t)nxt.pn * tstepB : cB;
;         for (int t = 0; t < nt; t += 2) {
;             const bool last = (t == nt - 2);
;             const char* a1 = cA + (size_t)(t + 1) * kstep;
;             const char* a2 = last ? nA : cA + (size_t)(t + 2) * kstep; const char* b2 = last ? nB : cB + (size_t)(t + 2) * kstep;
;             const char* a3 = a2 + kstep; const char* b3 = b2 + kstep;
;             PG8_LDB(B0, 0, 0); PG8_SCHED; PG8_LDA(At, 0, 0); PG8_STAGE(PG8_SA(1, 1), a1 + hstep, voffA);
;             PG8_WAIT_L(8); PG8_BAR; PG8_WAIT_L(0); PG8_MMA(0, 0, At, B0); PG8_BAR; PG8_SCHED;
;             PG8_LDB(B1, 0, 1); PG8_STAGE(PG8_SB(0, 0), b2, voffB);
;             PG8_BAR; PG8_WAIT_L(0); PG8_MMA(0, 1, At, B1); PG8_BAR;
;             PG8_LDA(At, 0, 1); PG8_STAGE(PG8_SA(0, 0), a2, voffA);
;             PG8_BAR; PG8_WAIT_L(0); PG8_MMA(1, 0, At, B0); PG8_BAR; PG8_SCHED;
;             PG8_STAGE(PG8_SB(0, 1), b2 + hstep, voffB);
;             PG8_WAIT_V(6); PG8_BAR; PG8_MMA(1, 1, At, B1); PG8_BAR;
;             PG8_LDB(B0, 1, 0); PG8_SCHED; PG8_LDA(At, 1, 0); PG8_STAGE(PG8_SA(0, 1), a2 + hstep, voffA);
;             PG8_WAIT_L(8); PG8_BAR; PG8_WAIT_L(0); PG8_MMA(0, 0, At, B0); PG8_BAR; PG8_SCHED;
;             PG8_LDB(B1, 1, 1); PG8_STAGE(PG8_SB(1, 0), b3, voffB);
;             PG8_BAR; PG8_WAIT_L(0); PG8_MMA(0, 1, At, B1); PG8_BAR;
;             PG8_LDA(At, 1, 1); PG8_STAGE(PG8_SA(1, 0), a3, voffA);
;             PG8_BAR; PG8_WAIT_L(0); PG8_MMA(1, 0, At, B0); PG8_BAR; PG8_SCHED;
;             PG8_STAGE(PG8_SB(1, 1), b3 + hstep, voffB);
;             PG8_WAIT_V(6); PG8_BAR; PG8_MMA(1, 1, At, B1); PG8_BAR;
.LBB0_845:
	s_ashr_i32 s37, s36, 31
	v_cmp_lt_i64_e32 vcc, s[38:39], v[158:159]
	s_lshl_b64 s[38:39], s[36:37], 19
	s_add_u32 s38, s54, s38
	s_addc_u32 s39, s55, s39
	s_and_b64 s[40:41], vcc, exec
	s_cselect_b32 s37, s39, s45
	s_cselect_b32 s43, s38, s44
	s_ashr_i32 s35, s34, 31
	s_lshl_b64 s[40:41], s[34:35], 19
	s_add_u32 s40, s56, s40
	s_addc_u32 s41, s57, s41
	s_and_b64 s[48:49], vcc, exec
	s_cselect_b32 s35, s41, s47
	s_cselect_b32 s79, s40, s46
	s_add_u32 s80, s46, 0x100
	s_addc_u32 s81, s47, 0
	s_mov_b32 s82, -2
	ds_read_b128 v[128:131], v165
	ds_read_b128 v[132:135], v165 offset:1024
	ds_read_b128 v[136:139], v165 offset:2048
	ds_read_b128 v[140:143], v165 offset:3072
	s_add_u32 s46, s44, 0x100
	s_addc_u32 s47, s45, 0
	s_cmp_eq_u32 s82, 12
	s_cselect_b32 s51, s37, s47
	s_cselect_b32 s50, s43, s46
	s_cselect_b32 s49, s35, s81
	s_cselect_b32 s48, s79, s80
	ds_read_b128 v[168:171], v166
	ds_read_b128 v[172:175], v166 offset:1024
	ds_read_b128 v[176:179], v166 offset:2048
	ds_read_b128 v[180:183], v166 offset:3072
	ds_read_b128 v[184:187], v166 offset:4096
	ds_read_b128 v[188:191], v166 offset:5120
	ds_read_b128 v[192:195], v166 offset:6144
	ds_read_b128 v[196:199], v166 offset:7168
	ds_read_b128 v[200:203], v167
	ds_read_b128 v[204:207], v167 offset:1024
	ds_read_b128 v[208:211], v167 offset:2048
	ds_read_b128 v[212:215], v167 offset:3072
	v_lshl_add_u64 v[252:253], s[44:45], 0, v[154:155]
	s_add_i32 m0, s59, 0xc000
	s_nop 0
	global_load_lds_dwordx4 v[252:253], off
	v_lshl_add_u64 v[252:253], s[44:45], 0, v[156:157]
	s_add_i32 m0, s59, 0xe000
	s_nop 0
	global_load_lds_dwordx4 v[252:253], off
	s_waitcnt vmcnt(8)
	s_waitcnt lgkmcnt(0)
	s_barrier
	s_setprio 1
	v_mfma_f32_16x16x32_bf16 v[124:127], v[128:131], v[168:171], 0
	v_mfma_f32_16x16x32_bf16 v[120:123], v[136:139], v[168:171], 0
	v_mfma_f32_16x16x32_bf16 v[116:119], v[128:131], v[176:179], 0
	v_mfma_f32_16x16x32_bf16 v[112:115], v[136:139], v[176:179], 0
	v_mfma_f32_16x16x32_bf16 v[108:111], v[128:131], v[184:187], 0
	v_mfma_f32_16x16x32_bf16 v[96:99], v[136:139], v[184:187], 0
	v_mfma_f32_16x16x32_bf16 v[80:83], v[128:131], v[192:195], 0
	v_mfma_f32_16x16x32_bf16 v[72:75], v[136:139], v[192:195], 0
	v_mfma_f32_16x16x32_bf16 v[124:127], v[132:135], v[172:175], v[124:127]
	v_mfma_f32_16x16x32_bf16 v[120:123], v[140:143], v[172:175], v[120:123]
	v_mfma_f32_16x16x32_bf16 v[116:119], v[132:135], v[180:183], v[116:119]
	v_mfma_f32_16x16x32_bf16 v[112:115], v[140:143], v[180:183], v[112:115]
	v_mfma_f32_16x16x32_bf16 v[108:111], v[132:135], v[188:191], v[108:111]
	v_mfma_f32_16x16x32_bf16 v[96:99], v[140:143], v[188:191], v[96:99]
	v_mfma_f32_16x16x32_bf16 v[80:83], v[132:135], v[196:199], v[80:83]
	v_mfma_f32_16x16x32_bf16 v[72:75], v[140:143], v[196:199], v[72:75]
	v_mfma_f32_16x16x32_bf16 v[104:107], v[200:203], v[168:171], 0
	v_mfma_f32_16x16x32_bf16 v[100:103], v[208:211], v[168:171], 0
	v_mfma_f32_16x16x32_bf16 v[92:95], v[200:203], v[176:179], 0
	v_mfma_f32_16x16x32_bf16 v[88:91], v[208:211], v[176:179], 0
	v_mfma_f32_16x16x32_bf16 v[84:87], v[200:203], v[184:187], 0
	v_mfma_f32_16x16x32_bf16 v[76:79], v[208:211], v[184:187], 0
	v_mfma_f32_16x16x32_bf16 v[68:71], v[200:203], v[192:195], 0
	v_mfma_f32_16x16x32_bf16 v[64:67], v[208:211], v[192:195], 0
	v_mfma_f32_16x16x32_bf16 v[104:107], v[204:207], v[172:175], v[104:107]
	v_mfma_f32_16x16x32_bf16 v[100:103], v[212:215], v[172:175], v[100:103]
	v_mfma_f32_16x16x32_bf16 v[92:95], v[204:207], v[180:183], v[92:95]
	v_mfma_f32_16x16x32_bf16 v[88:91], v[212:215], v[180:183], v[88:91]
	v_mfma_f32_16x16x32_bf16 v[84:87], v[204:207], v[188:191], v[84:87]
	v_mfma_f32_16x16x32_bf16 v[76:79], v[212:215], v[188:191], v[76:79]
	v_mfma_f32_16x16x32_bf16 v[68:71], v[204:207], v[196:199], v[68:71]
	v_mfma_f32_16x16x32_bf16 v[64:67], v[212:215], v[196:199], v[64:67]
	s_setprio 0
	s_barrier
	ds_read_b128 v[168:171], v166 offset:16384
	ds_read_b128 v[172:175], v166 offset:17408
	ds_read_b128 v[176:179], v166 offset:18432
	ds_read_b128 v[180:183], v166 offset:19456
	ds_read_b128 v[184:187], v166 offset:20480
	ds_read_b128 v[188:191], v166 offset:21504
	ds_read_b128 v[192:195], v166 offset:22528
	ds_read_b128 v[196:199], v166 offset:23552
	s_add_i32 s44, s72, s58
	v_lshl_add_u64 v[162:163], s[48:49], 0, v[146:147]
	s_mov_b32 m0, s44
	s_nop 0
	global_load_lds_dwordx4 v[162:163], off
	v_lshl_add_u64 v[216:217], s[48:49], 0, v[150:151]
	s_add_i32 m0, s44, 0x2000
	s_nop 0
	global_load_lds_dwordx4 v[216:217], off
	s_mov_b32 m0, s59
	v_lshl_add_u64 v[218:219], s[50:51], 0, v[144:145]
	global_load_lds_dwordx4 v[218:219], off
	v_lshl_add_u64 v[220:221], s[50:51], 0, v[148:149]
	s_mov_b32 m0, s60
	s_nop 0
	global_load_lds_dwordx4 v[220:221], off
	s_add_u32 s44, s48, 0x40000
	s_addc_u32 s45, s49, 0
	s_add_i32 s83, s73, s58
	v_lshl_add_u64 v[254:255], s[44:45], 0, v[146:147]
	s_mov_b32 m0, s83
	s_nop 0
	global_load_lds_dwordx4 v[254:255], off
	v_lshl_add_u64 v[254:255], s[44:45], 0, v[150:151]
	s_add_i32 m0, s83, 0x2000
	s_nop 0
	global_load_lds_dwordx4 v[254:255], off
	s_waitcnt vmcnt(8)
	s_waitcnt lgkmcnt(0)
	s_barrier
; #define PG8_STAGE(bufoff, gbase, voff) do { _Pragma("unroll") for (int _i = 0; _i < 2; ++_i) \
;         __builtin_amdgcn_global_load_lds((const unsigned*)((const char*)(gbase) + (voff)[_i]), (LAS unsigned*)(lds + (bufoff) + ldsw + _i * 8192), 16, 0, 0); } while (0)
; #define PG8_LDA(dst, b, h) do { _Pragma("unroll") for (int m = 0; m < 4; ++m) _Pragma("unroll") for (int k = 0; k < 2; ++k) dst[m][k] = *(const LAS bf16x8*)(lds + PG8_SA(b, h) + aoff + m * 2048 + k * 1024); } while (0)
; #define PG8_WAIT_V(n) asm volatile("s_waitcnt vmcnt(" #n ")" ::: "memory")
; #define PG8_WAIT_L(n) asm volatile("s_waitcnt lgkmcnt(" #n ")" ::: "memory")
; template <class Epi>
; __device__ __forceinline__ void gemm_phase(LAS unsigned char* lds, const Gemm g, const StaticOrder& S, const Epi& E, int wv) {
;     ...
;         for (int t = 0; t < nt; t += 2) {
;             const bool last = (t == nt - 2);
;             const char* a1 = cA + (size_t)(t + 1) * kstep;
;             const char* a2 = last ? nA : cA + (size_t)(t + 2) * kstep; const char* b2 = last ? nB : cB + (size_t)(t + 2) * kstep;
;             const char* a3 = a2 + kstep; const char* b3 = b2 + kstep;
;             PG8_LDB(B0, 0, 0); PG8_SCHED; PG8_LDA(At, 0, 0); PG8_STAGE(PG8_SA(1, 1), a1 + hstep, voffA);
;             PG8_WAIT_L(8); PG8_BAR; PG8_WAIT_L(0); PG8_MMA(0, 0, At, B0); PG8_BAR; PG8_SCHED;
;             PG8_LDB(B1, 0, 1); PG8_STAGE(PG8_SB(0, 0), b2, voffB);
;             PG8_BAR; PG8_WAIT_L(0); PG8_MMA(0, 1, At, B1); PG8_BAR;
;             PG8_LDA(At, 0, 1); PG8_STAGE(PG8_SA(0, 0), a2, voffA);
;             PG8_BAR; PG8_WAIT_L(0); PG8_MMA(1, 0, At, B0); PG8_BAR; PG8_SCHED;
;             PG8_STAGE(PG8_SB(0, 1), b2 + hstep, voffB);
;             PG8_WAIT_V(6); PG8_BAR; PG8_MMA(1, 1, At, B1); PG8_BAR;
;             PG8_LDB(B0, 1, 0); PG8_SCHED; PG8_LDA(At, 1, 0); PG8_STAGE(PG8_SA(0, 1), a2 + hstep, voffA);
;             PG8_WAIT_L(8); PG8_BAR; PG8_WAIT_L(0); PG8_MMA(0, 0, At, B0); PG8_BAR; PG8_SCHED;
;             PG8_LDB(B1, 1, 1); PG8_STAGE(PG8_SB(1, 0), b3, voffB);
;             PG8_BAR; PG8_WAIT_L(0); PG8_MMA(0, 1, At, B1); PG8_BAR;
;             PG8_LDA(At, 1, 1); PG8_STAGE(PG8_SA(1, 0), a3, voffA);
;             PG8_BAR; PG8_WAIT_L(0); PG8_MMA(1, 0, At, B0); PG8_BAR; PG8_SCHED;
;             PG8_STAGE(PG8_SB(1, 1), b3 + hstep, voffB);
;             PG8_WAIT_V(6); PG8_BAR; PG8_MMA(1, 1, At, B1); PG8_BAR;
	s_setprio 1
	v_mfma_f32_16x16x32_bf16 v[60:63], v[128:131], v[168:171], 0
	v_mfma_f32_16x16x32_bf16 v[56:59], v[136:139], v[168:171], 0
	v_mfma_f32_16x16x32_bf16 v[48:51], v[128:131], v[176:179], 0
	v_mfma_f32_16x16x32_bf16 v[40:43], v[136:139], v[176:179], 0
	v_mfma_f32_16x16x32_bf16 v[32:35], v[128:131], v[184:187], 0
	v_mfma_f32_16x16x32_bf16 v[24:27], v[136:139], v[184:187], 0
	v_mfma_f32_16x16x32_bf16 v[16:19], v[128:131], v[192:195], 0
	v_mfma_f32_16x16x32_bf16 v[8:11], v[136:139], v[192:195], 0
	v_mfma_f32_16x16x32_bf16 v[60:63], v[132:135], v[172:175], v[60:63]
	v_mfma_f32_16x16x32_bf16 v[56:59], v[140:143], v[172:175], v[56:59]
	v_mfma_f32_16x16x32_bf16 v[48:51], v[132:135], v[180:183], v[48:51]
	v_mfma_f32_16x16x32_bf16 v[40:43], v[140:143], v[180:183], v[40:43]
	v_mfma_f32_16x16x32_bf16 v[32:35], v[132:135], v[188:191], v[32:35]
	v_mfma_f32_16x16x32_bf16 v[24:27], v[140:143], v[188:191], v[24:27]
	v_mfma_f32_16x16x32_bf16 v[16:19], v[132:135], v[196:199], v[16:19]
	v_mfma_f32_16x16x32_bf16 v[8:11], v[140:143], v[196:199], v[8:11]
	v_mfma_f32_16x16x32_bf16 v[52:55], v[200:203], v[168:171], 0
	v_mfma_f32_16x16x32_bf16 v[44:47], v[208:211], v[168:171], 0
	v_mfma_f32_16x16x32_bf16 v[36:39], v[200:203], v[176:179], 0
	v_mfma_f32_16x16x32_bf16 v[28:31], v[208:211], v[176:179], 0
	v_mfma_f32_16x16x32_bf16 v[20:23], v[200:203], v[184:187], 0
	v_mfma_f32_16x16x32_bf16 v[12:15], v[208:211], v[184:187], 0
	v_mfma_f32_16x16x32_bf16 v[4:7], v[200:203], v[192:195], 0
	v_mfma_f32_16x16x32_bf16 v[0:3], v[208:211], v[192:195], 0
	v_mfma_f32_16x16x32_bf16 v[52:55], v[204:207], v[172:175], v[52:55]
	v_mfma_f32_16x16x32_bf16 v[44:47], v[212:215], v[172:175], v[44:47]
	v_mfma_f32_16x16x32_bf16 v[36:39], v[204:207], v[180:183], v[36:39]
	v_mfma_f32_16x16x32_bf16 v[28:31], v[212:215], v[180:183], v[28:31]
	v_mfma_f32_16x16x32_bf16 v[20:23], v[204:207], v[188:191], v[20:23]
	v_mfma_f32_16x16x32_bf16 v[12:15], v[212:215], v[188:191], v[12:15]
	v_mfma_f32_16x16x32_bf16 v[4:7], v[204:207], v[196:199], v[4:7]
	v_mfma_f32_16x16x32_bf16 v[0:3], v[212:215], v[196:199], v[0:3]
	s_setprio 0
	s_add_i32 s83, 0, 0x18000
	v_add_u32_e32 v140, s83, v164
	s_barrier
	ds_read_b128 v[128:131], v140
	ds_read_b128 v[132:135], v140 offset:1024
	ds_read_b128 v[136:139], v140 offset:2048
	ds_read_b128 v[140:143], v140 offset:3072
	s_add_u32 s44, s50, 0x40000
	s_addc_u32 s45, s51, 0
	ds_read_b128 v[168:171], v166 offset:32768
	ds_read_b128 v[172:175], v166 offset:33792
	ds_read_b128 v[176:179], v166 offset:34816
	ds_read_b128 v[180:183], v166 offset:35840
	ds_read_b128 v[184:187], v166 offset:36864
	ds_read_b128 v[188:191], v166 offset:37888
	ds_read_b128 v[192:195], v166 offset:38912
	ds_read_b128 v[196:199], v166 offset:39936
	s_mov_b32 m0, s61
	v_lshl_add_u64 v[252:253], s[44:45], 0, v[144:145]
	global_load_lds_dwordx4 v[252:253], off
	v_lshl_add_u64 v[252:253], s[44:45], 0, v[148:149]
	s_mov_b32 m0, s64
	s_nop 0
	global_load_lds_dwordx4 v[252:253], off
	s_add_i32 s50, 0, 0x1c000
	v_add_u32_e32 v152, s50, v164
	ds_read_b128 v[200:203], v152
	ds_read_b128 v[204:207], v152 offset:1024
	ds_read_b128 v[208:211], v152 offset:2048
	ds_read_b128 v[212:215], v152 offset:3072
	s_waitcnt vmcnt(8)
	s_waitcnt lgkmcnt(0)
	s_barrier
	s_setprio 1
	v_mfma_f32_16x16x32_bf16 v[124:127], v[128:131], v[168:171], v[124:127]
	v_mfma_f32_16x16x32_bf16 v[120:123], v[136:139], v[168:171], v[120:123]
	v_mfma_f32_16x16x32_bf16 v[116:119], v[128:131], v[176:179], v[116:119]
	v_mfma_f32_16x16x32_bf16 v[112:115], v[136:139], v[176:179], v[112:115]
	v_mfma_f32_16x16x32_bf16 v[108:111], v[128:131], v[184:187], v[108:111]
	v_mfma_f32_16x16x32_bf16 v[96:99], v[136:139], v[184:187], v[96:99]
	v_mfma_f32_16x16x32_bf16 v[80:83], v[128:131], v[192:195], v[80:83]
	v_mfma_f32_16x16x32_bf16 v[72:75], v[136:139], v[192:195], v[72:75]
	v_mfma_f32_16x16x32_bf16 v[124:127], v[132:135], v[172:175], v[124:127]
	v_mfma_f32_16x16x32_bf16 v[120:123], v[140:143], v[172:175], v[120:123]
	v_mfma_f32_16x16x32_bf16 v[116:119], v[132:135], v[180:183], v[116:119]
	v_mfma_f32_16x16x32_bf16 v[112:115], v[140:143], v[180:183], v[112:115]
	v_mfma_f32_16x16x32_bf16 v[108:111], v[132:135], v[188:191], v[108:111]
	v_mfma_f32_16x16x32_bf16 v[96:99], v[140:143], v[188:191], v[96:99]
	v_mfma_f32_16x16x32_bf16 v[80:83], v[132:135], v[196:199], v[80:83]
	v_mfma_f32_16x16x32_bf16 v[72:75], v[140:143], v[196:199], v[72:75]
	v_mfma_f32_16x16x32_bf16 v[104:107], v[200:203], v[168:171], v[104:107]
	v_mfma_f32_16x16x32_bf16 v[100:103], v[208:211], v[168:171], v[100:103]
	v_mfma_f32_16x16x32_bf16 v[92:95], v[200:203], v[176:179], v[92:95]
	v_mfma_f32_16x16x32_bf16 v[88:91], v[208:211], v[176:179], v[88:91]
	v_mfma_f32_16x16x32_bf16 v[84:87], v[200:203], v[184:187], v[84:87]
	v_mfma_f32_16x16x32_bf16 v[76:79], v[208:211], v[184:187], v[76:79]
	v_mfma_f32_16x16x32_bf16 v[68:71], v[200:203], v[192:195], v[68:71]
	v_mfma_f32_16x16x32_bf16 v[64:67], v[208:211], v[192:195], v[64:67]
	v_mfma_f32_16x16x32_bf16 v[104:107], v[204:207], v[172:175], v[104:107]
	v_mfma_f32_16x16x32_bf16 v[100:103], v[212:215], v[172:175], v[100:103]
	v_mfma_f32_16x16x32_bf16 v[92:95], v[204:207], v[180:183], v[92:95]
	v_mfma_f32_16x16x32_bf16 v[88:91], v[212:215], v[180:183], v[88:91]
	v_mfma_f32_16x16x32_bf16 v[84:87], v[204:207], v[188:191], v[84:87]
	v_mfma_f32_16x16x32_bf16 v[76:79], v[212:215], v[188:191], v[76:79]
	v_mfma_f32_16x16x32_bf16 v[68:71], v[204:207], v[196:199], v[68:71]
	v_mfma_f32_16x16x32_bf16 v[64:67], v[212:215], v[196:199], v[64:67]
	s_setprio 0
	s_barrier
; #define PG8_STAGE(bufoff, gbase, voff) do { _Pragma("unroll") for (int _i = 0; _i < 2; ++_i) \
;         __builtin_amdgcn_global_load_lds((const unsigned*)((const char*)(gbase) + (voff)[_i]), (LAS unsigned*)(lds + (bufoff) + ldsw + _i * 8192), 16, 0, 0); } while (0)
; #define PG8_LDA(dst, b, h) do { _Pragma("unroll") for (int m = 0; m < 4; ++m) _Pragma("unroll") for (int k = 0; k < 2; ++k) dst[m][k] = *(const LAS bf16x8*)(lds + PG8_SA(b, h) + aoff + m * 2048 + k * 1024); } while (0)
; #define PG8_WAIT_V(n) asm volatile("s_waitcnt vmcnt(" #n ")" ::: "memory")
; #define PG8_WAIT_L(n) asm volatile("s_waitcnt lgkmcnt(" #n ")" ::: "memory")
; template <class Epi>
; __device__ __forceinline__ void gemm_phase(LAS unsigned char* lds, const Gemm g, const StaticOrder& S, const Epi& E, int wv) {
;     ...
;         for (int t = 0; t < nt; t += 2) {
;             const bool last = (t == nt - 2);
;             const char* a1 = cA + (size_t)(t + 1) * kstep;
;             const char* a2 = last ? nA : cA + (size_t)(t + 2) * kstep; const char* b2 = last ? nB : cB + (size_t)(t + 2) * kstep;
;             const char* a3 = a2 + kstep; const char* b3 = b2 + kstep;
;             PG8_LDB(B0, 0, 0); PG8_SCHED; PG8_LDA(At, 0, 0); PG8_STAGE(PG8_SA(1, 1), a1 + hstep, voffA);
;             PG8_WAIT_L(8); PG8_BAR; PG8_WAIT_L(0); PG8_MMA(0, 0, At, B0); PG8_BAR; PG8_SCHED;
;             PG8_LDB(B1, 0, 1); PG8_STAGE(PG8_SB(0, 0), b2, voffB);
;             PG8_BAR; PG8_WAIT_L(0); PG8_MMA(0, 1, At, B1); PG8_BAR;
;             PG8_LDA(At, 0, 1); PG8_STAGE(PG8_SA(0, 0), a2, voffA);
;             PG8_BAR; PG8_WAIT_L(0); PG8_MMA(1, 0, At, B0); PG8_BAR; PG8_SCHED;
;             PG8_STAGE(PG8_SB(0, 1), b2 + hstep, voffB);
;             PG8_WAIT_V(6); PG8_BAR; PG8_MMA(1, 1, At, B1); PG8_BAR;
;             PG8_LDB(B0, 1, 0); PG8_SCHED; PG8_LDA(At, 1, 0); PG8_STAGE(PG8_SA(0, 1), a2 + hstep, voffA);
;             PG8_WAIT_L(8); PG8_BAR; PG8_WAIT_L(0); PG8_MMA(0, 0, At, B0); PG8_BAR; PG8_SCHED;
;             PG8_LDB(B1, 1, 1); PG8_STAGE(PG8_SB(1, 0), b3, voffB);
;             PG8_BAR; PG8_WAIT_L(0); PG8_MMA(0, 1, At, B1); PG8_BAR;
;             PG8_LDA(At, 1, 1); PG8_STAGE(PG8_SA(1, 0), a3, voffA);
;             PG8_BAR; PG8_WAIT_L(0); PG8_MMA(1, 0, At, B0); PG8_BAR; PG8_SCHED;
;             PG8_STAGE(PG8_SB(1, 1), b3 + hstep, voffB);
;             PG8_WAIT_V(6); PG8_BAR; PG8_MMA(1, 1, At, B1); PG8_BAR;
	ds_read_b128 v[168:171], v166 offset:49152
	ds_read_b128 v[172:175], v166 offset:50176
	ds_read_b128 v[176:179], v166 offset:51200
	ds_read_b128 v[180:183], v166 offset:52224
	ds_read_b128 v[184:187], v166 offset:53248
	ds_read_b128 v[188:191], v166 offset:54272
	ds_read_b128 v[192:195], v166 offset:55296
	ds_read_b128 v[196:199], v166 offset:56320
	s_add_i32 s44, s83, s58
	v_lshl_add_u64 v[162:163], v[162:163], 0, s[16:17]
	s_mov_b32 m0, s44
	s_nop 0
	global_load_lds_dwordx4 v[162:163], off
	v_lshl_add_u64 v[162:163], v[216:217], 0, s[16:17]
	s_add_i32 m0, s44, 0x2000
	s_nop 0
	global_load_lds_dwordx4 v[162:163], off
	s_mov_b32 m0, s67
	v_lshl_add_u64 v[162:163], v[218:219], 0, s[16:17]
	global_load_lds_dwordx4 v[162:163], off
	v_lshl_add_u64 v[162:163], v[220:221], 0, s[16:17]
	s_mov_b32 m0, s68
	s_nop 0
	global_load_lds_dwordx4 v[162:163], off
	s_add_u32 s44, s48, 0x40080
	s_addc_u32 s45, s49, 0
	s_add_i32 s48, s50, s58
	v_lshl_add_u64 v[254:255], s[44:45], 0, v[146:147]
	s_mov_b32 m0, s48
	s_nop 0
	global_load_lds_dwordx4 v[254:255], off
	v_lshl_add_u64 v[254:255], s[44:45], 0, v[150:151]
	s_add_i32 m0, s48, 0x2000
	s_nop 0
	global_load_lds_dwordx4 v[254:255], off
	s_waitcnt vmcnt(8)
	s_waitcnt lgkmcnt(0)
	s_barrier
	s_setprio 1
	v_mfma_f32_16x16x32_bf16 v[60:63], v[128:131], v[168:171], v[60:63]
	v_mfma_f32_16x16x32_bf16 v[56:59], v[136:139], v[168:171], v[56:59]
	v_mfma_f32_16x16x32_bf16 v[48:51], v[128:131], v[176:179], v[48:51]
	v_mfma_f32_16x16x32_bf16 v[40:43], v[136:139], v[176:179], v[40:43]
	v_mfma_f32_16x16x32_bf16 v[32:35], v[128:131], v[184:187], v[32:35]
	v_mfma_f32_16x16x32_bf16 v[24:27], v[136:139], v[184:187], v[24:27]
	v_mfma_f32_16x16x32_bf16 v[16:19], v[128:131], v[192:195], v[16:19]
	v_mfma_f32_16x16x32_bf16 v[8:11], v[136:139], v[192:195], v[8:11]
	v_mfma_f32_16x16x32_bf16 v[60:63], v[132:135], v[172:175], v[60:63]
	v_mfma_f32_16x16x32_bf16 v[56:59], v[140:143], v[172:175], v[56:59]
	v_mfma_f32_16x16x32_bf16 v[48:51], v[132:135], v[180:183], v[48:51]
	v_mfma_f32_16x16x32_bf16 v[40:43], v[140:143], v[180:183], v[40:43]
	v_mfma_f32_16x16x32_bf16 v[32:35], v[132:135], v[188:191], v[32:35]
	v_mfma_f32_16x16x32_bf16 v[24:27], v[140:143], v[188:191], v[24:27]
	v_mfma_f32_16x16x32_bf16 v[16:19], v[132:135], v[196:199], v[16:19]
	v_mfma_f32_16x16x32_bf16 v[8:11], v[140:143], v[196:199], v[8:11]
	v_mfma_f32_16x16x32_bf16 v[52:55], v[200:203], v[168:171], v[52:55]
	v_mfma_f32_16x16x32_bf16 v[44:47], v[208:211], v[168:171], v[44:47]
	v_mfma_f32_16x16x32_bf16 v[36:39], v[200:203], v[176:179], v[36:39]
	v_mfma_f32_16x16x32_bf16 v[28:31], v[208:211], v[176:179], v[28:31]
	v_mfma_f32_16x16x32_bf16 v[20:23], v[200:203], v[184:187], v[20:23]
	v_mfma_f32_16x16x32_bf16 v[12:15], v[208:211], v[184:187], v[12:15]
	v_mfma_f32_16x16x32_bf16 v[4:7], v[200:203], v[192:195], v[4:7]
	v_mfma_f32_16x16x32_bf16 v[0:3], v[208:211], v[192:195], v[0:3]
	v_mfma_f32_16x16x32_bf16 v[52:55], v[204:207], v[172:175], v[52:55]
	v_mfma_f32_16x16x32_bf16 v[44:47], v[212:215], v[172:175], v[44:47]
	v_mfma_f32_16x16x32_bf16 v[36:39], v[204:207], v[180:183], v[36:39]
	v_mfma_f32_16x16x32_bf16 v[28:31], v[212:215], v[180:183], v[28:31]
	v_mfma_f32_16x16x32_bf16 v[20:23], v[204:207], v[188:191], v[20:23]
	v_mfma_f32_16x16x32_bf16 v[12:15], v[212:215], v[188:191], v[12:15]
	v_mfma_f32_16x16x32_bf16 v[4:7], v[204:207], v[196:199], v[4:7]
	v_mfma_f32_16x16x32_bf16 v[0:3], v[212:215], v[196:199], v[0:3]
	s_setprio 0
	s_add_i32 s82, s82, 2
	s_add_u32 s80, s80, 0x100
	s_addc_u32 s81, s81, 0
	s_cmp_gt_u32 s82, 13
	s_mov_b64 s[44:45], s[46:47]
	s_barrier

; #define PG8_STAGE(bufoff, gbase, voff) do { _Pragma("unroll") for (int _i = 0; _i < 2; ++_i) \
;         __builtin_amdgcn_global_load_lds((const unsigned*)((const char*)(gbase) + (voff)[_i]), (LAS unsigned*)(lds + (bufoff) + ldsw + _i * 8192), 16, 0, 0); } while (0)
; #define PG8_WAIT_V(n) asm volatile("s_waitcnt vmcnt(" #n ")" ::: "memory")
; #define PG8_WAIT_L(n) asm volatile("s_waitcnt lgkmcnt(" #n ")" ::: "memory")
; template <class Epi>
; __device__ __forceinline__ void gemm_phase(LAS unsigned char* lds, const Gemm g, const StaticOrder& S, const Epi& E, int wv) {
;     ...
;         const bool has_next = S.next(ui + 1, nxt);
;         const char* nA = has_next ? (const char*)g.A + (size_t)nxt.pm * tstepA : cA; const char* nB = has_next ? (const char*)g.Bt + (size_t)nxt.pn * tstepB : cB;
;         for (int t = 0; t < nt; t += 2) {
;             const bool last = (t == nt - 2);
;             const char* a1 = cA + (size_t)(t + 1) * kstep;
;             const char* a2 = last ? nA : cA + (size_t)(t + 2) * kstep; const char* b2 = last ? nB : cB + (size_t)(t + 2) * kstep;
;             const char* a3 = a2 + kstep; const char* b3 = b2 + kstep;
;             PG8_LDB(B0, 0, 0); PG8_SCHED; PG8_LDA(At, 0, 0); PG8_STAGE(PG8_SA(1, 1), a1 + hstep, voffA);
;             PG8_WAIT_L(8); PG8_BAR; PG8_WAIT_L(0); PG8_MMA(0, 0, At, B0); PG8_BAR; PG8_SCHED;
;             PG8_LDB(B1, 0, 1); PG8_STAGE(PG8_SB(0, 0), b2, voffB);
;             PG8_BAR; PG8_WAIT_L(0); PG8_MMA(0, 1, At, B1); PG8_BAR;
;             PG8_LDA(At, 0, 1); PG8_STAGE(PG8_SA(0, 0), a2, voffA);
;             PG8_BAR; PG8_WAIT_L(0); PG8_MMA(1, 0, At, B0); PG8_BAR; PG8_SCHED;
;             PG8_STAGE(PG8_SB(0, 1), b2 + hstep, voffB);
;             PG8_WAIT_V(6); PG8_BAR; PG8_MMA(1, 1, At, B1); PG8_BAR;
;             PG8_LDB(B0, 1, 0); PG8_SCHED; PG8_LDA(At, 1, 0); PG8_STAGE(PG8_SA(0, 1), a2 + hstep, voffA);
;             PG8_WAIT_L(8); PG8_BAR; PG8_WAIT_L(0); PG8_MMA(0, 0, At, B0); PG8_BAR; PG8_SCHED;
;             PG8_LDB(B1, 1, 1); PG8_STAGE(PG8_SB(1, 0), b3, voffB);
;             PG8_BAR; PG8_WAIT_L(0); PG8_MMA(0, 1, At, B1); PG8_BAR;
;             PG8_LDA(At, 1, 1); PG8_STAGE(PG8_SA(1, 0), a3, voffA);
;             PG8_BAR; PG8_WAIT_L(0); PG8_MMA(1, 0, At, B0); PG8_BAR; PG8_SCHED;
;             PG8_STAGE(PG8_SB(1, 1), b3 + hstep, voffB);
;             PG8_WAIT_V(6); PG8_BAR; PG8_MMA(1, 1, At, B1); PG8_BAR;
.LBB0_998:
	s_ashr_i32 s41, s40, 31
	s_lshl_b64 s[16:17], s[40:41], 19
	s_add_u32 s44, s65, s16
	s_addc_u32 s45, s66, s17
	s_and_b64 s[6:7], s[6:7], exec
	s_cselect_b32 s9, s45, s15
	s_cselect_b32 s41, s44, s14
	s_add_u32 s46, s14, 0x100
	s_addc_u32 s48, s15, 0
	s_mov_b32 s49, -2
	s_waitcnt vmcnt(0)
	ds_read_b128 v[128:131], v214
	ds_read_b128 v[132:135], v214 offset:1024
	ds_read_b128 v[136:139], v214 offset:2048
	ds_read_b128 v[140:143], v214 offset:3072
	s_add_u32 s6, s12, 0x100
	s_addc_u32 s7, s13, 0
	s_cmp_eq_u32 s49, 12
	s_cselect_b32 s17, s43, s7
	s_cselect_b32 s16, s42, s6
	s_cselect_b32 s15, s9, s48
	s_cselect_b32 s14, s41, s46
	ds_read_b128 v[144:147], v215
	ds_read_b128 v[148:151], v215 offset:1024
	ds_read_b128 v[152:155], v215 offset:2048
	ds_read_b128 v[156:159], v215 offset:3072
	ds_read_b128 v[178:181], v215 offset:4096
	ds_read_b128 v[182:185], v215 offset:5120
	ds_read_b128 v[186:189], v215 offset:6144
	ds_read_b128 v[190:193], v215 offset:7168
	ds_read_b128 v[194:197], v216
	ds_read_b128 v[198:201], v216 offset:1024
	ds_read_b128 v[202:205], v216 offset:2048
	ds_read_b128 v[206:209], v216 offset:3072
	v_lshl_add_u64 v[252:253], s[12:13], 0, v[170:171]
	s_add_i32 m0, s68, 0xc000
	s_nop 0
	global_load_lds_dwordx4 v[252:253], off
	v_lshl_add_u64 v[252:253], s[12:13], 0, v[172:173]
	s_add_i32 m0, s68, 0xe000
	s_nop 0
	global_load_lds_dwordx4 v[252:253], off
	s_waitcnt vmcnt(8)
	s_waitcnt lgkmcnt(0)
	s_barrier
	s_setprio 1
	v_mfma_f32_16x16x32_bf16 v[124:127], v[128:131], v[144:147], 0
	v_mfma_f32_16x16x32_bf16 v[60:63], v[136:139], v[144:147], 0
	v_mfma_f32_16x16x32_bf16 v[116:119], v[128:131], v[152:155], 0
	v_mfma_f32_16x16x32_bf16 v[52:55], v[136:139], v[152:155], 0
	v_mfma_f32_16x16x32_bf16 v[112:115], v[128:131], v[178:181], 0
	v_mfma_f32_16x16x32_bf16 v[48:51], v[136:139], v[178:181], 0
	v_mfma_f32_16x16x32_bf16 v[108:111], v[128:131], v[186:189], 0
	v_mfma_f32_16x16x32_bf16 v[44:47], v[136:139], v[186:189], 0
	v_mfma_f32_16x16x32_bf16 v[124:127], v[132:135], v[148:151], v[124:127]
	v_mfma_f32_16x16x32_bf16 v[60:63], v[140:143], v[148:151], v[60:63]
	v_mfma_f32_16x16x32_bf16 v[116:119], v[132:135], v[156:159], v[116:119]
	v_mfma_f32_16x16x32_bf16 v[52:55], v[140:143], v[156:159], v[52:55]
	v_mfma_f32_16x16x32_bf16 v[112:115], v[132:135], v[182:185], v[112:115]
	v_mfma_f32_16x16x32_bf16 v[48:51], v[140:143], v[182:185], v[48:51]
	v_mfma_f32_16x16x32_bf16 v[108:111], v[132:135], v[190:193], v[108:111]
	v_mfma_f32_16x16x32_bf16 v[44:47], v[140:143], v[190:193], v[44:47]
	v_mfma_f32_16x16x32_bf16 v[120:123], v[194:197], v[144:147], 0
	v_mfma_f32_16x16x32_bf16 v[56:59], v[202:205], v[144:147], 0
	v_mfma_f32_16x16x32_bf16 v[104:107], v[194:197], v[152:155], 0
	v_mfma_f32_16x16x32_bf16 v[40:43], v[202:205], v[152:155], 0
	v_mfma_f32_16x16x32_bf16 v[100:103], v[194:197], v[178:181], 0
	v_mfma_f32_16x16x32_bf16 v[36:39], v[202:205], v[178:181], 0
	v_mfma_f32_16x16x32_bf16 v[96:99], v[194:197], v[186:189], 0
	v_mfma_f32_16x16x32_bf16 v[32:35], v[202:205], v[186:189], 0
	v_mfma_f32_16x16x32_bf16 v[120:123], v[198:201], v[148:151], v[120:123]
	v_mfma_f32_16x16x32_bf16 v[56:59], v[206:209], v[148:151], v[56:59]
	v_mfma_f32_16x16x32_bf16 v[104:107], v[198:201], v[156:159], v[104:107]
	v_mfma_f32_16x16x32_bf16 v[40:43], v[206:209], v[156:159], v[40:43]
	v_mfma_f32_16x16x32_bf16 v[100:103], v[198:201], v[182:185], v[100:103]
	v_mfma_f32_16x16x32_bf16 v[36:39], v[206:209], v[182:185], v[36:39]
	v_mfma_f32_16x16x32_bf16 v[96:99], v[198:201], v[190:193], v[96:99]
	v_mfma_f32_16x16x32_bf16 v[32:35], v[206:209], v[190:193], v[32:35]
	s_setprio 0
	s_barrier
	ds_read_b128 v[144:147], v215 offset:16384
	ds_read_b128 v[148:151], v215 offset:17408
	ds_read_b128 v[152:155], v215 offset:18432
	ds_read_b128 v[156:159], v215 offset:19456
	ds_read_b128 v[178:181], v215 offset:20480
	ds_read_b128 v[182:185], v215 offset:21504
	ds_read_b128 v[186:189], v215 offset:22528
	ds_read_b128 v[190:193], v215 offset:23552
	s_add_i32 s12, s90, s67
	v_lshl_add_u64 v[210:211], s[14:15], 0, v[162:163]
	s_mov_b32 m0, s12
	s_nop 0
	global_load_lds_dwordx4 v[210:211], off
	v_lshl_add_u64 v[220:221], s[14:15], 0, v[166:167]
	s_add_i32 m0, s12, 0x2000
	s_nop 0
	global_load_lds_dwordx4 v[220:221], off
	s_mov_b32 m0, s68
	v_lshl_add_u64 v[222:223], s[16:17], 0, v[160:161]
	global_load_lds_dwordx4 v[222:223], off
	v_lshl_add_u64 v[224:225], s[16:17], 0, v[164:165]
	s_mov_b32 m0, s69
	s_nop 0
	global_load_lds_dwordx4 v[224:225], off
	s_add_u32 s12, s14, 0x40000
	s_addc_u32 s13, s15, 0
	s_add_i32 s50, s91, s67
	v_lshl_add_u64 v[254:255], s[12:13], 0, v[162:163]
	s_mov_b32 m0, s50
	s_nop 0
	global_load_lds_dwordx4 v[254:255], off
	v_lshl_add_u64 v[254:255], s[12:13], 0, v[166:167]
	s_add_i32 m0, s50, 0x2000
	s_nop 0
	global_load_lds_dwordx4 v[254:255], off
	s_waitcnt vmcnt(8)
	s_waitcnt lgkmcnt(0)
	s_barrier
; #define PG8_STAGE(bufoff, gbase, voff) do { _Pragma("unroll") for (int _i = 0; _i < 2; ++_i) \
;         __builtin_amdgcn_global_load_lds((const unsigned*)((const char*)(gbase) + (voff)[_i]), (LAS unsigned*)(lds + (bufoff) + ldsw + _i * 8192), 16, 0, 0); } while (0)
; #define PG8_LDA(dst, b, h) do { _Pragma("unroll") for (int m = 0; m < 4; ++m) _Pragma("unroll") for (int k = 0; k < 2; ++k) dst[m][k] = *(const LAS bf16x8*)(lds + PG8_SA(b, h) + aoff + m * 2048 + k * 1024); } while (0)
; #define PG8_WAIT_V(n) asm volatile("s_waitcnt vmcnt(" #n ")" ::: "memory")
; #define PG8_WAIT_L(n) asm volatile("s_waitcnt lgkmcnt(" #n ")" ::: "memory")
; template <class Epi>
; __device__ __forceinline__ void gemm_phase(LAS unsigned char* lds, const Gemm g, const StaticOrder& S, const Epi& E, int wv) {
;     ...
;         for (int t = 0; t < nt; t += 2) {
;             const bool last = (t == nt - 2);
;             const char* a1 = cA + (size_t)(t + 1) * kstep;
;             const char* a2 = last ? nA : cA + (size_t)(t + 2) * kstep; const char* b2 = last ? nB : cB + (size_t)(t + 2) * kstep;
;             const char* a3 = a2 + kstep; const char* b3 = b2 + kstep;
;             PG8_LDB(B0, 0, 0); PG8_SCHED; PG8_LDA(At, 0, 0); PG8_STAGE(PG8_SA(1, 1), a1 + hstep, voffA);
;             PG8_WAIT_L(8); PG8_BAR; PG8_WAIT_L(0); PG8_MMA(0, 0, At, B0); PG8_BAR; PG8_SCHED;
;             PG8_LDB(B1, 0, 1); PG8_STAGE(PG8_SB(0, 0), b2, voffB);
;             PG8_BAR; PG8_WAIT_L(0); PG8_MMA(0, 1, At, B1); PG8_BAR;
;             PG8_LDA(At, 0, 1); PG8_STAGE(PG8_SA(0, 0), a2, voffA);
;             PG8_BAR; PG8_WAIT_L(0); PG8_MMA(1, 0, At, B0); PG8_BAR; PG8_SCHED;
;             PG8_STAGE(PG8_SB(0, 1), b2 + hstep, voffB);
;             PG8_WAIT_V(6); PG8_BAR; PG8_MMA(1, 1, At, B1); PG8_BAR;
;             PG8_LDB(B0, 1, 0); PG8_SCHED; PG8_LDA(At, 1, 0); PG8_STAGE(PG8_SA(0, 1), a2 + hstep, voffA);
;             PG8_WAIT_L(8); PG8_BAR; PG8_WAIT_L(0); PG8_MMA(0, 0, At, B0); PG8_BAR; PG8_SCHED;
;             PG8_LDB(B1, 1, 1); PG8_STAGE(PG8_SB(1, 0), b3, voffB);
;             PG8_BAR; PG8_WAIT_L(0); PG8_MMA(0, 1, At, B1); PG8_BAR;
;             PG8_LDA(At, 1, 1); PG8_STAGE(PG8_SA(1, 0), a3, voffA);
;             PG8_BAR; PG8_WAIT_L(0); PG8_MMA(1, 0, At, B0); PG8_BAR; PG8_SCHED;
;             PG8_STAGE(PG8_SB(1, 1), b3 + hstep, voffB);
;             PG8_WAIT_V(6); PG8_BAR; PG8_MMA(1, 1, At, B1); PG8_BAR;
	s_setprio 1
	v_mfma_f32_16x16x32_bf16 v[92:95], v[128:131], v[144:147], 0
	v_mfma_f32_16x16x32_bf16 v[28:31], v[136:139], v[144:147], 0
	v_mfma_f32_16x16x32_bf16 v[84:87], v[128:131], v[152:155], 0
	v_mfma_f32_16x16x32_bf16 v[20:23], v[136:139], v[152:155], 0
	v_mfma_f32_16x16x32_bf16 v[80:83], v[128:131], v[178:181], 0
	v_mfma_f32_16x16x32_bf16 v[16:19], v[136:139], v[178:181], 0
	v_mfma_f32_16x16x32_bf16 v[76:79], v[128:131], v[186:189], 0
	v_mfma_f32_16x16x32_bf16 v[12:15], v[136:139], v[186:189], 0
	v_mfma_f32_16x16x32_bf16 v[92:95], v[132:135], v[148:151], v[92:95]
	v_mfma_f32_16x16x32_bf16 v[28:31], v[140:143], v[148:151], v[28:31]
	v_mfma_f32_16x16x32_bf16 v[84:87], v[132:135], v[156:159], v[84:87]
	v_mfma_f32_16x16x32_bf16 v[20:23], v[140:143], v[156:159], v[20:23]
	v_mfma_f32_16x16x32_bf16 v[80:83], v[132:135], v[182:185], v[80:83]
	v_mfma_f32_16x16x32_bf16 v[16:19], v[140:143], v[182:185], v[16:19]
	v_mfma_f32_16x16x32_bf16 v[76:79], v[132:135], v[190:193], v[76:79]
	v_mfma_f32_16x16x32_bf16 v[12:15], v[140:143], v[190:193], v[12:15]
	v_mfma_f32_16x16x32_bf16 v[88:91], v[194:197], v[144:147], 0
	v_mfma_f32_16x16x32_bf16 v[24:27], v[202:205], v[144:147], 0
	v_mfma_f32_16x16x32_bf16 v[72:75], v[194:197], v[152:155], 0
	v_mfma_f32_16x16x32_bf16 v[8:11], v[202:205], v[152:155], 0
	v_mfma_f32_16x16x32_bf16 v[68:71], v[194:197], v[178:181], 0
	v_mfma_f32_16x16x32_bf16 v[4:7], v[202:205], v[178:181], 0
	v_mfma_f32_16x16x32_bf16 v[64:67], v[194:197], v[186:189], 0
	v_mfma_f32_16x16x32_bf16 v[0:3], v[202:205], v[186:189], 0
	v_mfma_f32_16x16x32_bf16 v[88:91], v[198:201], v[148:151], v[88:91]
	v_mfma_f32_16x16x32_bf16 v[24:27], v[206:209], v[148:151], v[24:27]
	v_mfma_f32_16x16x32_bf16 v[72:75], v[198:201], v[156:159], v[72:75]
	v_mfma_f32_16x16x32_bf16 v[8:11], v[206:209], v[156:159], v[8:11]
	v_mfma_f32_16x16x32_bf16 v[68:71], v[198:201], v[182:185], v[68:71]
	v_mfma_f32_16x16x32_bf16 v[4:7], v[206:209], v[182:185], v[4:7]
	v_mfma_f32_16x16x32_bf16 v[64:67], v[198:201], v[190:193], v[64:67]
	v_mfma_f32_16x16x32_bf16 v[0:3], v[206:209], v[190:193], v[0:3]
	s_setprio 0
	s_add_i32 s50, 0, 0x18000
	v_add_u32_e32 v140, s50, v213
	s_barrier
	ds_read_b128 v[128:131], v140
	ds_read_b128 v[132:135], v140 offset:1024
	ds_read_b128 v[136:139], v140 offset:2048
	ds_read_b128 v[140:143], v140 offset:3072
	s_add_u32 s12, s16, 0x40000
	s_addc_u32 s13, s17, 0
	ds_read_b128 v[144:147], v215 offset:32768
	ds_read_b128 v[148:151], v215 offset:33792
	ds_read_b128 v[152:155], v215 offset:34816
	ds_read_b128 v[156:159], v215 offset:35840
	ds_read_b128 v[178:181], v215 offset:36864
	ds_read_b128 v[182:185], v215 offset:37888
	ds_read_b128 v[186:189], v215 offset:38912
	ds_read_b128 v[190:193], v215 offset:39936
	s_mov_b32 m0, s70
	v_lshl_add_u64 v[252:253], s[12:13], 0, v[160:161]
	global_load_lds_dwordx4 v[252:253], off
	v_lshl_add_u64 v[252:253], s[12:13], 0, v[164:165]
	s_mov_b32 m0, s71
	s_nop 0
	global_load_lds_dwordx4 v[252:253], off
	s_add_i32 s16, 0, 0x1c000
	v_add_u32_e32 v168, s16, v213
	ds_read_b128 v[194:197], v168
	ds_read_b128 v[198:201], v168 offset:1024
	ds_read_b128 v[202:205], v168 offset:2048
	ds_read_b128 v[206:209], v168 offset:3072
	s_waitcnt vmcnt(8)
	s_waitcnt lgkmcnt(0)
	s_barrier
	s_setprio 1
	v_mfma_f32_16x16x32_bf16 v[124:127], v[128:131], v[144:147], v[124:127]
	v_mfma_f32_16x16x32_bf16 v[60:63], v[136:139], v[144:147], v[60:63]
	v_mfma_f32_16x16x32_bf16 v[116:119], v[128:131], v[152:155], v[116:119]
	v_mfma_f32_16x16x32_bf16 v[52:55], v[136:139], v[152:155], v[52:55]
	v_mfma_f32_16x16x32_bf16 v[112:115], v[128:131], v[178:181], v[112:115]
	v_mfma_f32_16x16x32_bf16 v[48:51], v[136:139], v[178:181], v[48:51]
	v_mfma_f32_16x16x32_bf16 v[108:111], v[128:131], v[186:189], v[108:111]
	v_mfma_f32_16x16x32_bf16 v[44:47], v[136:139], v[186:189], v[44:47]
	v_mfma_f32_16x16x32_bf16 v[124:127], v[132:135], v[148:151], v[124:127]
	v_mfma_f32_16x16x32_bf16 v[60:63], v[140:143], v[148:151], v[60:63]
	v_mfma_f32_16x16x32_bf16 v[116:119], v[132:135], v[156:159], v[116:119]
	v_mfma_f32_16x16x32_bf16 v[52:55], v[140:143], v[156:159], v[52:55]
	v_mfma_f32_16x16x32_bf16 v[112:115], v[132:135], v[182:185], v[112:115]
	v_mfma_f32_16x16x32_bf16 v[48:51], v[140:143], v[182:185], v[48:51]
	v_mfma_f32_16x16x32_bf16 v[108:111], v[132:135], v[190:193], v[108:111]
	v_mfma_f32_16x16x32_bf16 v[44:47], v[140:143], v[190:193], v[44:47]
	v_mfma_f32_16x16x32_bf16 v[120:123], v[194:197], v[144:147], v[120:123]
	v_mfma_f32_16x16x32_bf16 v[56:59], v[202:205], v[144:147], v[56:59]
	v_mfma_f32_16x16x32_bf16 v[104:107], v[194:197], v[152:155], v[104:107]
	v_mfma_f32_16x16x32_bf16 v[40:43], v[202:205], v[152:155], v[40:43]
	v_mfma_f32_16x16x32_bf16 v[100:103], v[194:197], v[178:181], v[100:103]
	v_mfma_f32_16x16x32_bf16 v[36:39], v[202:205], v[178:181], v[36:39]
	v_mfma_f32_16x16x32_bf16 v[96:99], v[194:197], v[186:189], v[96:99]
	v_mfma_f32_16x16x32_bf16 v[32:35], v[202:205], v[186:189], v[32:35]
	v_mfma_f32_16x16x32_bf16 v[120:123], v[198:201], v[148:151], v[120:123]
	v_mfma_f32_16x16x32_bf16 v[56:59], v[206:209], v[148:151], v[56:59]
	v_mfma_f32_16x16x32_bf16 v[104:107], v[198:201], v[156:159], v[104:107]
	v_mfma_f32_16x16x32_bf16 v[40:43], v[206:209], v[156:159], v[40:43]
	v_mfma_f32_16x16x32_bf16 v[100:103], v[198:201], v[182:185], v[100:103]
	v_mfma_f32_16x16x32_bf16 v[36:39], v[206:209], v[182:185], v[36:39]
	v_mfma_f32_16x16x32_bf16 v[96:99], v[198:201], v[190:193], v[96:99]
	v_mfma_f32_16x16x32_bf16 v[32:35], v[206:209], v[190:193], v[32:35]
	s_setprio 0
	s_barrier
; #define PG8_STAGE(bufoff, gbase, voff) do { _Pragma("unroll") for (int _i = 0; _i < 2; ++_i) \
;         __builtin_amdgcn_global_load_lds((const unsigned*)((const char*)(gbase) + (voff)[_i]), (LAS unsigned*)(lds + (bufoff) + ldsw + _i * 8192), 16, 0, 0); } while (0)
; #define PG8_LDA(dst, b, h) do { _Pragma("unroll") for (int m = 0; m < 4; ++m) _Pragma("unroll") for (int k = 0; k < 2; ++k) dst[m][k] = *(const LAS bf16x8*)(lds + PG8_SA(b, h) + aoff + m * 2048 + k * 1024); } while (0)
; #define PG8_WAIT_V(n) asm volatile("s_waitcnt vmcnt(" #n ")" ::: "memory")
; #define PG8_WAIT_L(n) asm volatile("s_waitcnt lgkmcnt(" #n ")" ::: "memory")
; template <class Epi>
; __device__ __forceinline__ void gemm_phase(LAS unsigned char* lds, const Gemm g, const StaticOrder& S, const Epi& E, int wv) {
;     ...
;         for (int t = 0; t < nt; t += 2) {
;             const bool last = (t == nt - 2);
;             const char* a1 = cA + (size_t)(t + 1) * kstep;
;             const char* a2 = last ? nA : cA + (size_t)(t + 2) * kstep; const char* b2 = last ? nB : cB + (size_t)(t + 2) * kstep;
;             const char* a3 = a2 + kstep; const char* b3 = b2 + kstep;
;             PG8_LDB(B0, 0, 0); PG8_SCHED; PG8_LDA(At, 0, 0); PG8_STAGE(PG8_SA(1, 1), a1 + hstep, voffA);
;             PG8_WAIT_L(8); PG8_BAR; PG8_WAIT_L(0); PG8_MMA(0, 0, At, B0); PG8_BAR; PG8_SCHED;
;             PG8_LDB(B1, 0, 1); PG8_STAGE(PG8_SB(0, 0), b2, voffB);
;             PG8_BAR; PG8_WAIT_L(0); PG8_MMA(0, 1, At, B1); PG8_BAR;
;             PG8_LDA(At, 0, 1); PG8_STAGE(PG8_SA(0, 0), a2, voffA);
;             PG8_BAR; PG8_WAIT_L(0); PG8_MMA(1, 0, At, B0); PG8_BAR; PG8_SCHED;
;             PG8_STAGE(PG8_SB(0, 1), b2 + hstep, voffB);
;             PG8_WAIT_V(6); PG8_BAR; PG8_MMA(1, 1, At, B1); PG8_BAR;
;             PG8_LDB(B0, 1, 0); PG8_SCHED; PG8_LDA(At, 1, 0); PG8_STAGE(PG8_SA(0, 1), a2 + hstep, voffA);
;             PG8_WAIT_L(8); PG8_BAR; PG8_WAIT_L(0); PG8_MMA(0, 0, At, B0); PG8_BAR; PG8_SCHED;
;             PG8_LDB(B1, 1, 1); PG8_STAGE(PG8_SB(1, 0), b3, voffB);
;             PG8_BAR; PG8_WAIT_L(0); PG8_MMA(0, 1, At, B1); PG8_BAR;
;             PG8_LDA(At, 1, 1); PG8_STAGE(PG8_SA(1, 0), a3, voffA);
;             PG8_BAR; PG8_WAIT_L(0); PG8_MMA(1, 0, At, B0); PG8_BAR; PG8_SCHED;
;             PG8_STAGE(PG8_SB(1, 1), b3 + hstep, voffB);
;             PG8_WAIT_V(6); PG8_BAR; PG8_MMA(1, 1, At, B1); PG8_BAR;
	ds_read_b128 v[144:147], v215 offset:49152
	ds_read_b128 v[148:151], v215 offset:50176
	ds_read_b128 v[152:155], v215 offset:51200
	ds_read_b128 v[156:159], v215 offset:52224
	ds_read_b128 v[178:181], v215 offset:53248
	ds_read_b128 v[182:185], v215 offset:54272
	ds_read_b128 v[186:189], v215 offset:55296
	ds_read_b128 v[190:193], v215 offset:56320
	s_add_i32 s12, s50, s67
	v_lshl_add_u64 v[210:211], v[210:211], 0, s[30:31]
	s_mov_b32 m0, s12
	s_nop 0
	global_load_lds_dwordx4 v[210:211], off
	v_lshl_add_u64 v[210:211], v[220:221], 0, s[30:31]
	s_add_i32 m0, s12, 0x2000
	s_nop 0
	global_load_lds_dwordx4 v[210:211], off
	s_mov_b32 m0, s77
	v_lshl_add_u64 v[210:211], v[222:223], 0, s[30:31]
	global_load_lds_dwordx4 v[210:211], off
	v_lshl_add_u64 v[210:211], v[224:225], 0, s[30:31]
	s_mov_b32 m0, s78
	s_nop 0
	global_load_lds_dwordx4 v[210:211], off
	s_add_u32 s12, s14, 0x40080
	s_addc_u32 s13, s15, 0
	s_add_i32 s14, s16, s67
	v_lshl_add_u64 v[254:255], s[12:13], 0, v[162:163]
	s_mov_b32 m0, s14
	s_nop 0
	global_load_lds_dwordx4 v[254:255], off
	v_lshl_add_u64 v[254:255], s[12:13], 0, v[166:167]
	s_add_i32 m0, s14, 0x2000
	s_nop 0
	global_load_lds_dwordx4 v[254:255], off
	s_waitcnt vmcnt(8)
	s_waitcnt lgkmcnt(0)
	s_barrier
	s_setprio 1
	v_mfma_f32_16x16x32_bf16 v[92:95], v[128:131], v[144:147], v[92:95]
	v_mfma_f32_16x16x32_bf16 v[28:31], v[136:139], v[144:147], v[28:31]
	v_mfma_f32_16x16x32_bf16 v[84:87], v[128:131], v[152:155], v[84:87]
	v_mfma_f32_16x16x32_bf16 v[20:23], v[136:139], v[152:155], v[20:23]
	v_mfma_f32_16x16x32_bf16 v[80:83], v[128:131], v[178:181], v[80:83]
	v_mfma_f32_16x16x32_bf16 v[16:19], v[136:139], v[178:181], v[16:19]
	v_mfma_f32_16x16x32_bf16 v[76:79], v[128:131], v[186:189], v[76:79]
	v_mfma_f32_16x16x32_bf16 v[12:15], v[136:139], v[186:189], v[12:15]
	v_mfma_f32_16x16x32_bf16 v[92:95], v[132:135], v[148:151], v[92:95]
	v_mfma_f32_16x16x32_bf16 v[28:31], v[140:143], v[148:151], v[28:31]
	v_mfma_f32_16x16x32_bf16 v[84:87], v[132:135], v[156:159], v[84:87]
	v_mfma_f32_16x16x32_bf16 v[20:23], v[140:143], v[156:159], v[20:23]
	v_mfma_f32_16x16x32_bf16 v[80:83], v[132:135], v[182:185], v[80:83]
	v_mfma_f32_16x16x32_bf16 v[16:19], v[140:143], v[182:185], v[16:19]
	v_mfma_f32_16x16x32_bf16 v[76:79], v[132:135], v[190:193], v[76:79]
	v_mfma_f32_16x16x32_bf16 v[12:15], v[140:143], v[190:193], v[12:15]
	v_mfma_f32_16x16x32_bf16 v[88:91], v[194:197], v[144:147], v[88:91]
	v_mfma_f32_16x16x32_bf16 v[24:27], v[202:205], v[144:147], v[24:27]
	v_mfma_f32_16x16x32_bf16 v[72:75], v[194:197], v[152:155], v[72:75]
	v_mfma_f32_16x16x32_bf16 v[8:11], v[202:205], v[152:155], v[8:11]
	v_mfma_f32_16x16x32_bf16 v[68:71], v[194:197], v[178:181], v[68:71]
	v_mfma_f32_16x16x32_bf16 v[4:7], v[202:205], v[178:181], v[4:7]
	v_mfma_f32_16x16x32_bf16 v[64:67], v[194:197], v[186:189], v[64:67]
	v_mfma_f32_16x16x32_bf16 v[0:3], v[202:205], v[186:189], v[0:3]
	v_mfma_f32_16x16x32_bf16 v[88:91], v[198:201], v[148:151], v[88:91]
	v_mfma_f32_16x16x32_bf16 v[24:27], v[206:209], v[148:151], v[24:27]
	v_mfma_f32_16x16x32_bf16 v[72:75], v[198:201], v[156:159], v[72:75]
	v_mfma_f32_16x16x32_bf16 v[8:11], v[206:209], v[156:159], v[8:11]
	v_mfma_f32_16x16x32_bf16 v[68:71], v[198:201], v[182:185], v[68:71]
	v_mfma_f32_16x16x32_bf16 v[4:7], v[206:209], v[182:185], v[4:7]
	v_mfma_f32_16x16x32_bf16 v[64:67], v[198:201], v[190:193], v[64:67]
	v_mfma_f32_16x16x32_bf16 v[0:3], v[206:209], v[190:193], v[0:3]
	s_setprio 0
	s_add_i32 s49, s49, 2
	s_add_u32 s46, s46, 0x100
	s_addc_u32 s48, s48, 0
	s_cmp_gt_u32 s49, 13
	s_mov_b64 s[12:13], s[6:7]
	s_barrier

; #define PG8_STAGE(bufoff, gbase, voff) do { _Pragma("unroll") for (int _i = 0; _i < 2; ++_i) \
;         __builtin_amdgcn_global_load_lds((const unsigned*)((const char*)(gbase) + (voff)[_i]), (LAS unsigned*)(lds + (bufoff) + ldsw + _i * 8192), 16, 0, 0); } while (0)
; #define PG8_WAIT_V(n) asm volatile("s_waitcnt vmcnt(" #n ")" ::: "memory")
; #define PG8_WAIT_L(n) asm volatile("s_waitcnt lgkmcnt(" #n ")" ::: "memory")
; template <class Epi>
; __device__ __forceinline__ void gemm_phase(LAS unsigned char* lds, const Gemm g, const StaticOrder& S, const Epi& E, int wv) {
;     ...
;         const bool has_next = S.next(ui + 1, nxt);
;         const char* nA = has_next ? (const char*)g.A + (size_t)nxt.pm * tstepA : cA; const char* nB = has_next ? (const char*)g.Bt + (size_t)nxt.pn * tstepB : cB;
;         for (int t = 0; t < nt; t += 2) {
;             const bool last = (t == nt - 2);
;             const char* a1 = cA + (size_t)(t + 1) * kstep;
;             const char* a2 = last ? nA : cA + (size_t)(t + 2) * kstep; const char* b2 = last ? nB : cB + (size_t)(t + 2) * kstep;
;             const char* a3 = a2 + kstep; const char* b3 = b2 + kstep;
;             PG8_LDB(B0, 0, 0); PG8_SCHED; PG8_LDA(At, 0, 0); PG8_STAGE(PG8_SA(1, 1), a1 + hstep, voffA);
;             PG8_WAIT_L(8); PG8_BAR; PG8_WAIT_L(0); PG8_MMA(0, 0, At, B0); PG8_BAR; PG8_SCHED;
;             PG8_LDB(B1, 0, 1); PG8_STAGE(PG8_SB(0, 0), b2, voffB);
;             PG8_BAR; PG8_WAIT_L(0); PG8_MMA(0, 1, At, B1); PG8_BAR;
;             PG8_LDA(At, 0, 1); PG8_STAGE(PG8_SA(0, 0), a2, voffA);
;             PG8_BAR; PG8_WAIT_L(0); PG8_MMA(1, 0, At, B0); PG8_BAR; PG8_SCHED;
;             PG8_STAGE(PG8_SB(0, 1), b2 + hstep, voffB);
;             PG8_WAIT_V(6); PG8_BAR; PG8_MMA(1, 1, At, B1); PG8_BAR;
;             PG8_LDB(B0, 1, 0); PG8_SCHED; PG8_LDA(At, 1, 0); PG8_STAGE(PG8_SA(0, 1), a2 + hstep, voffA);
;             PG8_WAIT_L(8); PG8_BAR; PG8_WAIT_L(0); PG8_MMA(0, 0, At, B0); PG8_BAR; PG8_SCHED;
;             PG8_LDB(B1, 1, 1); PG8_STAGE(PG8_SB(1, 0), b3, voffB);
;             PG8_BAR; PG8_WAIT_L(0); PG8_MMA(0, 1, At, B1); PG8_BAR;
;             PG8_LDA(At, 1, 1); PG8_STAGE(PG8_SA(1, 0), a3, voffA);
;             PG8_BAR; PG8_WAIT_L(0); PG8_MMA(1, 0, At, B0); PG8_BAR; PG8_SCHED;
;             PG8_STAGE(PG8_SB(1, 1), b3 + hstep, voffB);
;             PG8_WAIT_V(6); PG8_BAR; PG8_MMA(1, 1, At, B1); PG8_BAR;
.LBB0_1121:
	s_add_u32 s38, s38, 0xb0080
	s_addc_u32 s39, s39, 0
	s_add_u32 s37, s40, 0x100
	s_addc_u32 s73, s41, 0
	s_mov_b32 s74, -2
	ds_read_b128 v[128:131], v165
	ds_read_b128 v[132:135], v165 offset:1024
	ds_read_b128 v[136:139], v165 offset:2048
	ds_read_b128 v[140:143], v165 offset:3072
	s_add_u32 s40, s38, 0xfff50080
	s_addc_u32 s41, s39, -1
	s_cmp_eq_u32 s74, 40
	s_cselect_b32 s43, s5, s41
	s_cselect_b32 s42, s4, s40
	s_cselect_b32 s41, s7, s73
	s_cselect_b32 s40, s6, s37
	ds_read_b128 v[168:171], v166
	ds_read_b128 v[172:175], v166 offset:1024
	ds_read_b128 v[176:179], v166 offset:2048
	ds_read_b128 v[180:183], v166 offset:3072
	ds_read_b128 v[184:187], v166 offset:4096
	ds_read_b128 v[188:191], v166 offset:5120
	ds_read_b128 v[192:195], v166 offset:6144
	ds_read_b128 v[196:199], v166 offset:7168
	ds_read_b128 v[200:203], v167
	ds_read_b128 v[204:207], v167 offset:1024
	ds_read_b128 v[208:211], v167 offset:2048
	ds_read_b128 v[212:215], v167 offset:3072
	v_lshl_add_u64 v[252:253], s[38:39], 0, v[154:155]
	s_add_i32 m0, s51, 0xc000
	s_nop 0
	global_load_lds_dwordx4 v[252:253], off
	v_lshl_add_u64 v[252:253], s[38:39], 0, v[156:157]
	s_add_i32 m0, s51, 0xe000
	s_nop 0
	global_load_lds_dwordx4 v[252:253], off
	s_waitcnt vmcnt(8)
	s_waitcnt lgkmcnt(0)
	s_barrier
	s_setprio 1
	v_mfma_f32_16x16x32_bf16 v[124:127], v[128:131], v[168:171], 0
	v_mfma_f32_16x16x32_bf16 v[120:123], v[136:139], v[168:171], 0
	v_mfma_f32_16x16x32_bf16 v[116:119], v[128:131], v[176:179], 0
	v_mfma_f32_16x16x32_bf16 v[112:115], v[136:139], v[176:179], 0
	v_mfma_f32_16x16x32_bf16 v[108:111], v[128:131], v[184:187], 0
	v_mfma_f32_16x16x32_bf16 v[96:99], v[136:139], v[184:187], 0
	v_mfma_f32_16x16x32_bf16 v[80:83], v[128:131], v[192:195], 0
	v_mfma_f32_16x16x32_bf16 v[72:75], v[136:139], v[192:195], 0
	v_mfma_f32_16x16x32_bf16 v[124:127], v[132:135], v[172:175], v[124:127]
	v_mfma_f32_16x16x32_bf16 v[120:123], v[140:143], v[172:175], v[120:123]
	v_mfma_f32_16x16x32_bf16 v[116:119], v[132:135], v[180:183], v[116:119]
	v_mfma_f32_16x16x32_bf16 v[112:115], v[140:143], v[180:183], v[112:115]
	v_mfma_f32_16x16x32_bf16 v[108:111], v[132:135], v[188:191], v[108:111]
	v_mfma_f32_16x16x32_bf16 v[96:99], v[140:143], v[188:191], v[96:99]
	v_mfma_f32_16x16x32_bf16 v[80:83], v[132:135], v[196:199], v[80:83]
	v_mfma_f32_16x16x32_bf16 v[72:75], v[140:143], v[196:199], v[72:75]
	v_mfma_f32_16x16x32_bf16 v[104:107], v[200:203], v[168:171], 0
	v_mfma_f32_16x16x32_bf16 v[100:103], v[208:211], v[168:171], 0
	v_mfma_f32_16x16x32_bf16 v[92:95], v[200:203], v[176:179], 0
	v_mfma_f32_16x16x32_bf16 v[88:91], v[208:211], v[176:179], 0
	v_mfma_f32_16x16x32_bf16 v[84:87], v[200:203], v[184:187], 0
	v_mfma_f32_16x16x32_bf16 v[76:79], v[208:211], v[184:187], 0
	v_mfma_f32_16x16x32_bf16 v[68:71], v[200:203], v[192:195], 0
	v_mfma_f32_16x16x32_bf16 v[64:67], v[208:211], v[192:195], 0
	v_mfma_f32_16x16x32_bf16 v[104:107], v[204:207], v[172:175], v[104:107]
	v_mfma_f32_16x16x32_bf16 v[100:103], v[212:215], v[172:175], v[100:103]
	v_mfma_f32_16x16x32_bf16 v[92:95], v[204:207], v[180:183], v[92:95]
	v_mfma_f32_16x16x32_bf16 v[88:91], v[212:215], v[180:183], v[88:91]
	v_mfma_f32_16x16x32_bf16 v[84:87], v[204:207], v[188:191], v[84:87]
	v_mfma_f32_16x16x32_bf16 v[76:79], v[212:215], v[188:191], v[76:79]
	v_mfma_f32_16x16x32_bf16 v[68:71], v[204:207], v[196:199], v[68:71]
	v_mfma_f32_16x16x32_bf16 v[64:67], v[212:215], v[196:199], v[64:67]
	s_setprio 0
	s_barrier
	ds_read_b128 v[168:171], v166 offset:16384
	ds_read_b128 v[172:175], v166 offset:17408
	ds_read_b128 v[176:179], v166 offset:18432
	ds_read_b128 v[180:183], v166 offset:19456
	ds_read_b128 v[184:187], v166 offset:20480
	ds_read_b128 v[188:191], v166 offset:21504
	ds_read_b128 v[192:195], v166 offset:22528
	ds_read_b128 v[196:199], v166 offset:23552
	s_add_i32 s75, s64, s50
	v_lshl_add_u64 v[162:163], s[40:41], 0, v[146:147]
	s_mov_b32 m0, s75
	s_nop 0
	global_load_lds_dwordx4 v[162:163], off
	v_lshl_add_u64 v[216:217], s[40:41], 0, v[150:151]
	s_add_i32 m0, s75, 0x2000
	s_nop 0
	global_load_lds_dwordx4 v[216:217], off
	s_mov_b32 m0, s51
	v_lshl_add_u64 v[218:219], s[42:43], 0, v[144:145]
	global_load_lds_dwordx4 v[218:219], off
	v_lshl_add_u64 v[220:221], s[42:43], 0, v[148:149]
	s_mov_b32 m0, s52
	s_nop 0
	global_load_lds_dwordx4 v[220:221], off
	s_add_u32 s76, s40, 0xb0000
	s_addc_u32 s77, s41, 0
	s_add_i32 s75, s65, s50
	v_lshl_add_u64 v[254:255], s[76:77], 0, v[146:147]
	s_mov_b32 m0, s75
	s_nop 0
	global_load_lds_dwordx4 v[254:255], off
	v_lshl_add_u64 v[254:255], s[76:77], 0, v[150:151]
	s_add_i32 m0, s75, 0x2000
	s_nop 0
	global_load_lds_dwordx4 v[254:255], off
	s_waitcnt vmcnt(8)
	s_waitcnt lgkmcnt(0)
	s_barrier
; #define PG8_STAGE(bufoff, gbase, voff) do { _Pragma("unroll") for (int _i = 0; _i < 2; ++_i) \
;         __builtin_amdgcn_global_load_lds((const unsigned*)((const char*)(gbase) + (voff)[_i]), (LAS unsigned*)(lds + (bufoff) + ldsw + _i * 8192), 16, 0, 0); } while (0)
; #define PG8_LDA(dst, b, h) do { _Pragma("unroll") for (int m = 0; m < 4; ++m) _Pragma("unroll") for (int k = 0; k < 2; ++k) dst[m][k] = *(const LAS bf16x8*)(lds + PG8_SA(b, h) + aoff + m * 2048 + k * 1024); } while (0)
; #define PG8_WAIT_V(n) asm volatile("s_waitcnt vmcnt(" #n ")" ::: "memory")
; #define PG8_WAIT_L(n) asm volatile("s_waitcnt lgkmcnt(" #n ")" ::: "memory")
; template <class Epi>
; __device__ __forceinline__ void gemm_phase(LAS unsigned char* lds, const Gemm g, const StaticOrder& S, const Epi& E, int wv) {
;     ...
;         for (int t = 0; t < nt; t += 2) {
;             const bool last = (t == nt - 2);
;             const char* a1 = cA + (size_t)(t + 1) * kstep;
;             const char* a2 = last ? nA : cA + (size_t)(t + 2) * kstep; const char* b2 = last ? nB : cB + (size_t)(t + 2) * kstep;
;             const char* a3 = a2 + kstep; const char* b3 = b2 + kstep;
;             PG8_LDB(B0, 0, 0); PG8_SCHED; PG8_LDA(At, 0, 0); PG8_STAGE(PG8_SA(1, 1), a1 + hstep, voffA);
;             PG8_WAIT_L(8); PG8_BAR; PG8_WAIT_L(0); PG8_MMA(0, 0, At, B0); PG8_BAR; PG8_SCHED;
;             PG8_LDB(B1, 0, 1); PG8_STAGE(PG8_SB(0, 0), b2, voffB);
;             PG8_BAR; PG8_WAIT_L(0); PG8_MMA(0, 1, At, B1); PG8_BAR;
;             PG8_LDA(At, 0, 1); PG8_STAGE(PG8_SA(0, 0), a2, voffA);
;             PG8_BAR; PG8_WAIT_L(0); PG8_MMA(1, 0, At, B0); PG8_BAR; PG8_SCHED;
;             PG8_STAGE(PG8_SB(0, 1), b2 + hstep, voffB);
;             PG8_WAIT_V(6); PG8_BAR; PG8_MMA(1, 1, At, B1); PG8_BAR;
;             PG8_LDB(B0, 1, 0); PG8_SCHED; PG8_LDA(At, 1, 0); PG8_STAGE(PG8_SA(0, 1), a2 + hstep, voffA);
;             PG8_WAIT_L(8); PG8_BAR; PG8_WAIT_L(0); PG8_MMA(0, 0, At, B0); PG8_BAR; PG8_SCHED;
;             PG8_LDB(B1, 1, 1); PG8_STAGE(PG8_SB(1, 0), b3, voffB);
;             PG8_BAR; PG8_WAIT_L(0); PG8_MMA(0, 1, At, B1); PG8_BAR;
;             PG8_LDA(At, 1, 1); PG8_STAGE(PG8_SA(1, 0), a3, voffA);
;             PG8_BAR; PG8_WAIT_L(0); PG8_MMA(1, 0, At, B0); PG8_BAR; PG8_SCHED;
;             PG8_STAGE(PG8_SB(1, 1), b3 + hstep, voffB);
;             PG8_WAIT_V(6); PG8_BAR; PG8_MMA(1, 1, At, B1); PG8_BAR;
	s_setprio 1
	v_mfma_f32_16x16x32_bf16 v[60:63], v[128:131], v[168:171], 0
	v_mfma_f32_16x16x32_bf16 v[56:59], v[136:139], v[168:171], 0
	v_mfma_f32_16x16x32_bf16 v[48:51], v[128:131], v[176:179], 0
	v_mfma_f32_16x16x32_bf16 v[40:43], v[136:139], v[176:179], 0
	v_mfma_f32_16x16x32_bf16 v[32:35], v[128:131], v[184:187], 0
	v_mfma_f32_16x16x32_bf16 v[24:27], v[136:139], v[184:187], 0
	v_mfma_f32_16x16x32_bf16 v[16:19], v[128:131], v[192:195], 0
	v_mfma_f32_16x16x32_bf16 v[8:11], v[136:139], v[192:195], 0
	v_mfma_f32_16x16x32_bf16 v[60:63], v[132:135], v[172:175], v[60:63]
	v_mfma_f32_16x16x32_bf16 v[56:59], v[140:143], v[172:175], v[56:59]
	v_mfma_f32_16x16x32_bf16 v[48:51], v[132:135], v[180:183], v[48:51]
	v_mfma_f32_16x16x32_bf16 v[40:43], v[140:143], v[180:183], v[40:43]
	v_mfma_f32_16x16x32_bf16 v[32:35], v[132:135], v[188:191], v[32:35]
	v_mfma_f32_16x16x32_bf16 v[24:27], v[140:143], v[188:191], v[24:27]
	v_mfma_f32_16x16x32_bf16 v[16:19], v[132:135], v[196:199], v[16:19]
	v_mfma_f32_16x16x32_bf16 v[8:11], v[140:143], v[196:199], v[8:11]
	v_mfma_f32_16x16x32_bf16 v[52:55], v[200:203], v[168:171], 0
	v_mfma_f32_16x16x32_bf16 v[44:47], v[208:211], v[168:171], 0
	v_mfma_f32_16x16x32_bf16 v[36:39], v[200:203], v[176:179], 0
	v_mfma_f32_16x16x32_bf16 v[28:31], v[208:211], v[176:179], 0
	v_mfma_f32_16x16x32_bf16 v[20:23], v[200:203], v[184:187], 0
	v_mfma_f32_16x16x32_bf16 v[12:15], v[208:211], v[184:187], 0
	v_mfma_f32_16x16x32_bf16 v[4:7], v[200:203], v[192:195], 0
	v_mfma_f32_16x16x32_bf16 v[0:3], v[208:211], v[192:195], 0
	v_mfma_f32_16x16x32_bf16 v[52:55], v[204:207], v[172:175], v[52:55]
	v_mfma_f32_16x16x32_bf16 v[44:47], v[212:215], v[172:175], v[44:47]
	v_mfma_f32_16x16x32_bf16 v[36:39], v[204:207], v[180:183], v[36:39]
	v_mfma_f32_16x16x32_bf16 v[28:31], v[212:215], v[180:183], v[28:31]
	v_mfma_f32_16x16x32_bf16 v[20:23], v[204:207], v[188:191], v[20:23]
	v_mfma_f32_16x16x32_bf16 v[12:15], v[212:215], v[188:191], v[12:15]
	v_mfma_f32_16x16x32_bf16 v[4:7], v[204:207], v[196:199], v[4:7]
	v_mfma_f32_16x16x32_bf16 v[0:3], v[212:215], v[196:199], v[0:3]
	s_setprio 0
	s_add_i32 s75, 0, 0x18000
	v_add_u32_e32 v140, s75, v164
	s_barrier
	ds_read_b128 v[128:131], v140
	ds_read_b128 v[132:135], v140 offset:1024
	ds_read_b128 v[136:139], v140 offset:2048
	ds_read_b128 v[140:143], v140 offset:3072
	s_add_u32 s42, s42, 0xb0000
	s_addc_u32 s43, s43, 0
	ds_read_b128 v[168:171], v166 offset:32768
	ds_read_b128 v[172:175], v166 offset:33792
	ds_read_b128 v[176:179], v166 offset:34816
	ds_read_b128 v[180:183], v166 offset:35840
	ds_read_b128 v[184:187], v166 offset:36864
	ds_read_b128 v[188:191], v166 offset:37888
	ds_read_b128 v[192:195], v166 offset:38912
	ds_read_b128 v[196:199], v166 offset:39936
	s_mov_b32 m0, s53
	v_lshl_add_u64 v[252:253], s[42:43], 0, v[144:145]
	global_load_lds_dwordx4 v[252:253], off
	v_lshl_add_u64 v[252:253], s[42:43], 0, v[148:149]
	s_mov_b32 m0, s54
	s_nop 0
	global_load_lds_dwordx4 v[252:253], off
	s_add_i32 s42, 0, 0x1c000
	v_add_u32_e32 v152, s42, v164
	ds_read_b128 v[200:203], v152
	ds_read_b128 v[204:207], v152 offset:1024
	ds_read_b128 v[208:211], v152 offset:2048
	ds_read_b128 v[212:215], v152 offset:3072
	s_waitcnt vmcnt(8)
	s_waitcnt lgkmcnt(0)
	s_barrier
	s_setprio 1
	v_mfma_f32_16x16x32_bf16 v[124:127], v[128:131], v[168:171], v[124:127]
	v_mfma_f32_16x16x32_bf16 v[120:123], v[136:139], v[168:171], v[120:123]
	v_mfma_f32_16x16x32_bf16 v[116:119], v[128:131], v[176:179], v[116:119]
	v_mfma_f32_16x16x32_bf16 v[112:115], v[136:139], v[176:179], v[112:115]
	v_mfma_f32_16x16x32_bf16 v[108:111], v[128:131], v[184:187], v[108:111]
	v_mfma_f32_16x16x32_bf16 v[96:99], v[136:139], v[184:187], v[96:99]
	v_mfma_f32_16x16x32_bf16 v[80:83], v[128:131], v[192:195], v[80:83]
	v_mfma_f32_16x16x32_bf16 v[72:75], v[136:139], v[192:195], v[72:75]
	v_mfma_f32_16x16x32_bf16 v[124:127], v[132:135], v[172:175], v[124:127]
	v_mfma_f32_16x16x32_bf16 v[120:123], v[140:143], v[172:175], v[120:123]
	v_mfma_f32_16x16x32_bf16 v[116:119], v[132:135], v[180:183], v[116:119]
	v_mfma_f32_16x16x32_bf16 v[112:115], v[140:143], v[180:183], v[112:115]
	v_mfma_f32_16x16x32_bf16 v[108:111], v[132:135], v[188:191], v[108:111]
	v_mfma_f32_16x16x32_bf16 v[96:99], v[140:143], v[188:191], v[96:99]
	v_mfma_f32_16x16x32_bf16 v[80:83], v[132:135], v[196:199], v[80:83]
	v_mfma_f32_16x16x32_bf16 v[72:75], v[140:143], v[196:199], v[72:75]
	v_mfma_f32_16x16x32_bf16 v[104:107], v[200:203], v[168:171], v[104:107]
	v_mfma_f32_16x16x32_bf16 v[100:103], v[208:211], v[168:171], v[100:103]
	v_mfma_f32_16x16x32_bf16 v[92:95], v[200:203], v[176:179], v[92:95]
	v_mfma_f32_16x16x32_bf16 v[88:91], v[208:211], v[176:179], v[88:91]
	v_mfma_f32_16x16x32_bf16 v[84:87], v[200:203], v[184:187], v[84:87]
	v_mfma_f32_16x16x32_bf16 v[76:79], v[208:211], v[184:187], v[76:79]
	v_mfma_f32_16x16x32_bf16 v[68:71], v[200:203], v[192:195], v[68:71]
	v_mfma_f32_16x16x32_bf16 v[64:67], v[208:211], v[192:195], v[64:67]
	v_mfma_f32_16x16x32_bf16 v[104:107], v[204:207], v[172:175], v[104:107]
	v_mfma_f32_16x16x32_bf16 v[100:103], v[212:215], v[172:175], v[100:103]
	v_mfma_f32_16x16x32_bf16 v[92:95], v[204:207], v[180:183], v[92:95]
	v_mfma_f32_16x16x32_bf16 v[88:91], v[212:215], v[180:183], v[88:91]
	v_mfma_f32_16x16x32_bf16 v[84:87], v[204:207], v[188:191], v[84:87]
	v_mfma_f32_16x16x32_bf16 v[76:79], v[212:215], v[188:191], v[76:79]
	v_mfma_f32_16x16x32_bf16 v[68:71], v[204:207], v[196:199], v[68:71]
	v_mfma_f32_16x16x32_bf16 v[64:67], v[212:215], v[196:199], v[64:67]
	s_setprio 0
	s_barrier
; #define PG8_STAGE(bufoff, gbase, voff) do { _Pragma("unroll") for (int _i = 0; _i < 2; ++_i) \
;         __builtin_amdgcn_global_load_lds((const unsigned*)((const char*)(gbase) + (voff)[_i]), (LAS unsigned*)(lds + (bufoff) + ldsw + _i * 8192), 16, 0, 0); } while (0)
; #define PG8_LDA(dst, b, h) do { _Pragma("unroll") for (int m = 0; m < 4; ++m) _Pragma("unroll") for (int k = 0; k < 2; ++k) dst[m][k] = *(const LAS bf16x8*)(lds + PG8_SA(b, h) + aoff + m * 2048 + k * 1024); } while (0)
; #define PG8_WAIT_V(n) asm volatile("s_waitcnt vmcnt(" #n ")" ::: "memory")
; #define PG8_WAIT_L(n) asm volatile("s_waitcnt lgkmcnt(" #n ")" ::: "memory")
; template <class Epi>
; __device__ __forceinline__ void gemm_phase(LAS unsigned char* lds, const Gemm g, const StaticOrder& S, const Epi& E, int wv) {
;     ...
;         for (int t = 0; t < nt; t += 2) {
;             const bool last = (t == nt - 2);
;             const char* a1 = cA + (size_t)(t + 1) * kstep;
;             const char* a2 = last ? nA : cA + (size_t)(t + 2) * kstep; const char* b2 = last ? nB : cB + (size_t)(t + 2) * kstep;
;             const char* a3 = a2 + kstep; const char* b3 = b2 + kstep;
;             PG8_LDB(B0, 0, 0); PG8_SCHED; PG8_LDA(At, 0, 0); PG8_STAGE(PG8_SA(1, 1), a1 + hstep, voffA);
;             PG8_WAIT_L(8); PG8_BAR; PG8_WAIT_L(0); PG8_MMA(0, 0, At, B0); PG8_BAR; PG8_SCHED;
;             PG8_LDB(B1, 0, 1); PG8_STAGE(PG8_SB(0, 0), b2, voffB);
;             PG8_BAR; PG8_WAIT_L(0); PG8_MMA(0, 1, At, B1); PG8_BAR;
;             PG8_LDA(At, 0, 1); PG8_STAGE(PG8_SA(0, 0), a2, voffA);
;             PG8_BAR; PG8_WAIT_L(0); PG8_MMA(1, 0, At, B0); PG8_BAR; PG8_SCHED;
;             PG8_STAGE(PG8_SB(0, 1), b2 + hstep, voffB);
;             PG8_WAIT_V(6); PG8_BAR; PG8_MMA(1, 1, At, B1); PG8_BAR;
;             PG8_LDB(B0, 1, 0); PG8_SCHED; PG8_LDA(At, 1, 0); PG8_STAGE(PG8_SA(0, 1), a2 + hstep, voffA);
;             PG8_WAIT_L(8); PG8_BAR; PG8_WAIT_L(0); PG8_MMA(0, 0, At, B0); PG8_BAR; PG8_SCHED;
;             PG8_LDB(B1, 1, 1); PG8_STAGE(PG8_SB(1, 0), b3, voffB);
;             PG8_BAR; PG8_WAIT_L(0); PG8_MMA(0, 1, At, B1); PG8_BAR;
;             PG8_LDA(At, 1, 1); PG8_STAGE(PG8_SA(1, 0), a3, voffA);
;             PG8_BAR; PG8_WAIT_L(0); PG8_MMA(1, 0, At, B0); PG8_BAR; PG8_SCHED;
;             PG8_STAGE(PG8_SB(1, 1), b3 + hstep, voffB);
;             PG8_WAIT_V(6); PG8_BAR; PG8_MMA(1, 1, At, B1); PG8_BAR;
	ds_read_b128 v[168:171], v166 offset:49152
	ds_read_b128 v[172:175], v166 offset:50176
	ds_read_b128 v[176:179], v166 offset:51200
	ds_read_b128 v[180:183], v166 offset:52224
	ds_read_b128 v[184:187], v166 offset:53248
	ds_read_b128 v[188:191], v166 offset:54272
	ds_read_b128 v[192:195], v166 offset:55296
	ds_read_b128 v[196:199], v166 offset:56320
	s_add_i32 s43, s75, s50
	v_lshl_add_u64 v[162:163], v[162:163], 0, s[16:17]
	s_mov_b32 m0, s43
	s_nop 0
	global_load_lds_dwordx4 v[162:163], off
	v_lshl_add_u64 v[162:163], v[216:217], 0, s[16:17]
	s_add_i32 m0, s43, 0x2000
	s_nop 0
	global_load_lds_dwordx4 v[162:163], off
	s_mov_b32 m0, s57
	v_lshl_add_u64 v[162:163], v[218:219], 0, s[16:17]
	global_load_lds_dwordx4 v[162:163], off
	v_lshl_add_u64 v[162:163], v[220:221], 0, s[16:17]
	s_mov_b32 m0, s58
	s_nop 0
	global_load_lds_dwordx4 v[162:163], off
	s_add_u32 s40, s40, 0xb0080
	s_addc_u32 s41, s41, 0
	s_add_i32 s42, s42, s50
	v_lshl_add_u64 v[254:255], s[40:41], 0, v[146:147]
	s_mov_b32 m0, s42
	s_nop 0
	global_load_lds_dwordx4 v[254:255], off
	v_lshl_add_u64 v[254:255], s[40:41], 0, v[150:151]
	s_add_i32 m0, s42, 0x2000
	s_nop 0
	global_load_lds_dwordx4 v[254:255], off
	s_waitcnt vmcnt(8)
	s_waitcnt lgkmcnt(0)
	s_barrier
	s_setprio 1
	v_mfma_f32_16x16x32_bf16 v[60:63], v[128:131], v[168:171], v[60:63]
	v_mfma_f32_16x16x32_bf16 v[56:59], v[136:139], v[168:171], v[56:59]
	v_mfma_f32_16x16x32_bf16 v[48:51], v[128:131], v[176:179], v[48:51]
	v_mfma_f32_16x16x32_bf16 v[40:43], v[136:139], v[176:179], v[40:43]
	v_mfma_f32_16x16x32_bf16 v[32:35], v[128:131], v[184:187], v[32:35]
	v_mfma_f32_16x16x32_bf16 v[24:27], v[136:139], v[184:187], v[24:27]
	v_mfma_f32_16x16x32_bf16 v[16:19], v[128:131], v[192:195], v[16:19]
	v_mfma_f32_16x16x32_bf16 v[8:11], v[136:139], v[192:195], v[8:11]
	v_mfma_f32_16x16x32_bf16 v[60:63], v[132:135], v[172:175], v[60:63]
	v_mfma_f32_16x16x32_bf16 v[56:59], v[140:143], v[172:175], v[56:59]
	v_mfma_f32_16x16x32_bf16 v[48:51], v[132:135], v[180:183], v[48:51]
	v_mfma_f32_16x16x32_bf16 v[40:43], v[140:143], v[180:183], v[40:43]
	v_mfma_f32_16x16x32_bf16 v[32:35], v[132:135], v[188:191], v[32:35]
	v_mfma_f32_16x16x32_bf16 v[24:27], v[140:143], v[188:191], v[24:27]
	v_mfma_f32_16x16x32_bf16 v[16:19], v[132:135], v[196:199], v[16:19]
	v_mfma_f32_16x16x32_bf16 v[8:11], v[140:143], v[196:199], v[8:11]
	v_mfma_f32_16x16x32_bf16 v[52:55], v[200:203], v[168:171], v[52:55]
	v_mfma_f32_16x16x32_bf16 v[44:47], v[208:211], v[168:171], v[44:47]
	v_mfma_f32_16x16x32_bf16 v[36:39], v[200:203], v[176:179], v[36:39]
	v_mfma_f32_16x16x32_bf16 v[28:31], v[208:211], v[176:179], v[28:31]
	v_mfma_f32_16x16x32_bf16 v[20:23], v[200:203], v[184:187], v[20:23]
	v_mfma_f32_16x16x32_bf16 v[12:15], v[208:211], v[184:187], v[12:15]
	v_mfma_f32_16x16x32_bf16 v[4:7], v[200:203], v[192:195], v[4:7]
	v_mfma_f32_16x16x32_bf16 v[0:3], v[208:211], v[192:195], v[0:3]
	v_mfma_f32_16x16x32_bf16 v[52:55], v[204:207], v[172:175], v[52:55]
	v_mfma_f32_16x16x32_bf16 v[44:47], v[212:215], v[172:175], v[44:47]
	v_mfma_f32_16x16x32_bf16 v[36:39], v[204:207], v[180:183], v[36:39]
	v_mfma_f32_16x16x32_bf16 v[28:31], v[212:215], v[180:183], v[28:31]
	v_mfma_f32_16x16x32_bf16 v[20:23], v[204:207], v[188:191], v[20:23]
	v_mfma_f32_16x16x32_bf16 v[12:15], v[212:215], v[188:191], v[12:15]
	v_mfma_f32_16x16x32_bf16 v[4:7], v[204:207], v[196:199], v[4:7]
	v_mfma_f32_16x16x32_bf16 v[0:3], v[212:215], v[196:199], v[0:3]
	s_setprio 0
	s_add_i32 s74, s74, 2
	s_add_u32 s38, s38, 0x100
	s_addc_u32 s39, s39, 0
	s_add_u32 s37, s37, 0x100
	s_addc_u32 s73, s73, 0
	s_cmp_gt_u32 s74, 41
	s_barrier
